# norm phases: 64-lane sum via DPP row ops + permlane16/32 swap instead of six ds_bpermute round trips
# baseline (speedup 1.0000x reference)
; __device__ __forceinline__ float wave_sum(float v) {
; #pragma unroll
;     for (int o = 1; o < 64; o <<= 1) v += __shfl_xor(v, o);
;     return v;
; }
; __device__ __forceinline__ void rms_store_bf16(const f32x4 (&v)[4], const float* g, bf16_t* orow, int lane) {
;     float s = 0.f;
; #pragma unroll
;     for (int j = 0; j < 4; ++j) s += (v[j].x * v[j].x + v[j].y * v[j].y) + (v[j].z * v[j].z + v[j].w * v[j].w);
;     const float rs = 1.f / sqrtf(wave_sum(s) * (1.f / 1024.f) + EPS);
;     unsigned long long* o8 = (unsigned long long*)orow + lane;
; #pragma unroll
;     for (int j = 0; j < 4; ++j) { const f32x4 gg = *((const f32x4*)g + lane + 64 * j);
;         o8[64 * j] = (unsigned long long)pk2(v[j].x * rs * gg.x, v[j].y * rs * gg.y) | ((unsigned long long)pk2(v[j].z * rs * gg.z, v[j].w * rs * gg.w) << 32); }
; }
; __global__ void __launch_bounds__(NTHR, 2) hymba_fwd(Params P) {
;     ...
;         for (int t0 = gw; t0 < TT; t0 += 2 * NGW) {
;             f32x4 v[2][4]; int tt[2];
; #pragma unroll
;             for (int u = 0; u < 2; ++u) { const int t = t0 + u * NGW; tt[u] = t; const int tc = t < TT ? t : TT - 1;
;                 const int b = tc / LL, p = tc - b * LL;
;                 const float* src = (p < NMETA) ? P.meta + (size_t)p * 1024 : P.x + ((size_t)b * SEQ + p - NMETA) * 1024;
; #pragma unroll
;                 for (int j = 0; j < 4; ++j) v[u][j] = __builtin_nontemporal_load((const f32x4*)src + lane + 64 * j); }
; #pragma unroll
;             for (int u = 0; u < 2; ++u) { const int t = tt[u];
;                 if (t < TT) rms_store_bf16(v[u], P.mix_pre_g, XN + (size_t)t * 1024, lane); }
;         }
.LBB0_47:
	s_waitcnt vmcnt(3)
	v_pk_mul_f32 v[6:7], v[28:29], v[28:29]
	v_pk_mul_f32 v[8:9], v[26:27], v[26:27]
	global_load_dwordx4 v[30:33], v43, s[0:1] nt
	global_load_dwordx4 v[22:25], v43, s[0:1] offset:1024 nt
	v_pk_mov_b32 v[14:15], v[8:9], v[6:7] op_sel:[1,0]
	v_mov_b32_e32 v9, v7
	v_pk_add_f32 v[6:7], v[14:15], v[8:9]
	s_waitcnt vmcnt(4)
	v_pk_mul_f32 v[8:9], v[20:21], v[20:21]
	v_pk_mul_f32 v[14:15], v[18:19], v[18:19]
	v_pk_add_f32 v[6:7], v[6:7], v[6:7] op_sel:[0,1] op_sel_hi:[1,0]
	v_pk_mov_b32 v[16:17], v[14:15], v[8:9] op_sel:[1,0]
	v_mov_b32_e32 v15, v9
	v_pk_add_f32 v[8:9], v[16:17], v[14:15]
	s_waitcnt vmcnt(2)
	v_mul_f32_e32 v14, v2, v2
	v_mul_f32_e32 v15, v3, v3
	v_pk_add_f32 v[8:9], v[8:9], v[8:9] op_sel:[0,1] op_sel_hi:[1,0]
	v_mov_b32_e32 v7, v14
	v_mov_b32_e32 v9, v15
	v_pk_add_f32 v[6:7], v[6:7], v[8:9]
	v_mul_f32_e32 v8, v11, v11
	v_mul_f32_e32 v14, v13, v13
	v_mul_f32_e32 v16, v4, v4
	v_mul_f32_e32 v17, v5, v5
	v_pk_fma_f32 v[8:9], v[10:11], v[10:11], v[8:9] op_sel_hi:[1,1,0]
	v_pk_fma_f32 v[14:15], v[12:13], v[12:13], v[14:15] op_sel_hi:[1,1,0]
	v_mov_b32_e32 v9, v16
	v_mov_b32_e32 v15, v17
	v_pk_add_f32 v[8:9], v[8:9], v[14:15]
	s_ashr_i32 s7, s6, 31
	v_pk_add_f32 v[6:7], v[6:7], v[8:9]
	s_lshl_b64 s[10:11], s[6:7], 11
	v_add_f32_e32 v6, v6, v7
	s_cmp_gt_i32 s8, 0x807f
	s_nop 1
	v_add_f32_dpp v6, v6, v6 quad_perm:[1,0,3,2] row_mask:0xf bank_mask:0xf
	s_nop 1
	v_add_f32_dpp v6, v6, v6 quad_perm:[2,3,0,1] row_mask:0xf bank_mask:0xf
	s_nop 1
	v_add_f32_dpp v6, v6, v6 row_half_mirror row_mask:0xf bank_mask:0xf
	s_nop 1
	v_add_f32_dpp v6, v6, v6 row_mirror row_mask:0xf bank_mask:0xf
	v_mov_b32_e32 v7, v6
	s_nop 1
	v_permlane16_swap_b32 v7, v6
	v_add_f32_e32 v6, v6, v7
	v_mov_b32_e32 v7, v6
	s_nop 1
	v_permlane32_swap_b32 v7, v6
	v_add_f32_e32 v6, v6, v7
	v_fmamk_f32 v6, v6, 0x3a800000, v44
	v_mul_f32_e32 v7, 0x4f800000, v6
	v_cmp_gt_f32_e32 vcc, s15, v6
	s_nop 1
	v_cndmask_b32_e32 v50, v6, v7, vcc
	v_sqrt_f32_e32 v51, v50
	global_load_dwordx4 v[14:17], v43, s[0:1] offset:2048 nt
	global_load_dwordx4 v[6:9], v43, s[0:1] offset:3072 nt
	v_add_u32_e32 v52, -1, v51
	v_add_u32_e32 v53, 1, v51
	v_fma_f32 v54, -v52, v51, v50
	v_fma_f32 v55, -v53, v51, v50
	v_cmp_ge_f32_e64 s[0:1], 0, v54
	s_nop 1
	v_cndmask_b32_e64 v51, v51, v52, s[0:1]
	v_cmp_lt_f32_e64 s[0:1], 0, v55
	s_nop 1
	v_cndmask_b32_e64 v51, v51, v53, s[0:1]
	v_mul_f32_e32 v52, 0x37800000, v51
	v_cndmask_b32_e32 v51, v51, v52, vcc
	v_cmp_class_f32_e32 vcc, v50, v45
	s_nop 1
	v_cndmask_b32_e32 v52, v51, v50, vcc
	v_div_scale_f32 v53, s[0:1], v52, v52, 1.0
	v_rcp_f32_e32 v54, v53
	v_div_scale_f32 v55, vcc, 1.0, v52, 1.0
	v_lshl_add_u64 v[50:51], v[34:35], 0, s[10:11]
	v_fma_f32 v56, -v53, v54, 1.0
	v_fmac_f32_e32 v54, v56, v54
	v_mul_f32_e32 v56, v55, v54
	v_fma_f32 v57, -v53, v56, v55
	v_fmac_f32_e32 v56, v57, v54
	v_fma_f32 v53, -v53, v56, v55
	v_div_fmas_f32 v53, v53, v54, v56
	v_div_fixup_f32 v52, v53, v52, 1.0
	v_pk_mul_f32 v[26:27], v[26:27], v[52:53] op_sel_hi:[1,0]
	v_pk_mul_f32 v[28:29], v[28:29], v[52:53] op_sel_hi:[1,0]
	s_waitcnt vmcnt(4)
	v_pk_mul_f32 v[26:27], v[64:65], v[26:27]
	v_pk_mul_f32 v[28:29], v[66:67], v[28:29]
	v_cvt_pk_bf16_f32 v26, v26, v27
	v_cvt_pk_bf16_f32 v27, v28, v29
	global_store_dwordx2 v[50:51], v[26:27], off
	v_pk_mul_f32 v[18:19], v[18:19], v[52:53] op_sel_hi:[1,0]
	v_pk_mul_f32 v[20:21], v[20:21], v[52:53] op_sel_hi:[1,0]
	v_pk_mul_f32 v[10:11], v[10:11], v[52:53] op_sel_hi:[1,0]
	v_pk_mul_f32 v[12:13], v[12:13], v[52:53] op_sel_hi:[1,0]
	v_pk_mul_f32 v[2:3], v[2:3], v[52:53] op_sel_hi:[1,0]
	v_pk_mul_f32 v[4:5], v[4:5], v[52:53] op_sel_hi:[1,0]
	v_pk_mul_f32 v[18:19], v[68:69], v[18:19]
	v_pk_mul_f32 v[20:21], v[70:71], v[20:21]
	v_cvt_pk_bf16_f32 v18, v18, v19
	v_cvt_pk_bf16_f32 v19, v20, v21
	global_store_dwordx2 v[50:51], v[18:19], off offset:512
	v_pk_mul_f32 v[10:11], v[72:73], v[10:11]
	v_pk_mul_f32 v[12:13], v[74:75], v[12:13]
	v_cvt_pk_bf16_f32 v10, v10, v11
	v_cvt_pk_bf16_f32 v11, v12, v13
	global_store_dwordx2 v[50:51], v[10:11], off offset:1024
	v_pk_mul_f32 v[2:3], v[76:77], v[2:3]
	v_pk_mul_f32 v[4:5], v[78:79], v[4:5]
	v_cvt_pk_bf16_f32 v2, v2, v3
	v_cvt_pk_bf16_f32 v3, v4, v5
	global_store_dwordx2 v[50:51], v[2:3], off offset:1536
	s_cbranch_scc1 .LBB0_38
; __device__ __forceinline__ float wave_sum(float v) {
; #pragma unroll
;     for (int o = 1; o < 64; o <<= 1) v += __shfl_xor(v, o);
;     return v;
; }
; __device__ __forceinline__ void rms_store_bf16(const f32x4 (&v)[4], const float* g, bf16_t* orow, int lane) {
;     float s = 0.f;
; #pragma unroll
;     for (int j = 0; j < 4; ++j) s += (v[j].x * v[j].x + v[j].y * v[j].y) + (v[j].z * v[j].z + v[j].w * v[j].w);
;     const float rs = 1.f / sqrtf(wave_sum(s) * (1.f / 1024.f) + EPS);
;     unsigned long long* o8 = (unsigned long long*)orow + lane;
; #pragma unroll
;     for (int j = 0; j < 4; ++j) { const f32x4 gg = *((const f32x4*)g + lane + 64 * j);
;         o8[64 * j] = (unsigned long long)pk2(v[j].x * rs * gg.x, v[j].y * rs * gg.y) | ((unsigned long long)pk2(v[j].z * rs * gg.z, v[j].w * rs * gg.w) << 32); }
; }
; __global__ void __launch_bounds__(NTHR, 2) hymba_fwd(Params P) {
;     ...
;         for (int t0 = gw; t0 < TT; t0 += 2 * NGW) {
;             f32x4 v[2][4]; int tt[2];
; #pragma unroll
;             for (int u = 0; u < 2; ++u) { const int t = t0 + u * NGW; tt[u] = t; const int tc = t < TT ? t : TT - 1;
;                 const int b = tc / LL, p = tc - b * LL;
;                 const float* src = (p < NMETA) ? P.meta + (size_t)p * 1024 : P.x + ((size_t)b * SEQ + p - NMETA) * 1024;
; #pragma unroll
;                 for (int j = 0; j < 4; ++j) v[u][j] = __builtin_nontemporal_load((const f32x4*)src + lane + 64 * j); }
; #pragma unroll
;             for (int u = 0; u < 2; ++u) { const int t = tt[u];
;                 if (t < TT) rms_store_bf16(v[u], P.mix_pre_g, XN + (size_t)t * 1024, lane); }
;         }
	s_waitcnt vmcnt(4)
	v_pk_mul_f32 v[2:3], v[32:33], v[32:33]
	v_pk_mul_f32 v[4:5], v[30:31], v[30:31]
	v_mul_f32_e32 v18, v8, v8
	v_pk_mov_b32 v[10:11], v[4:5], v[2:3] op_sel:[1,0]
	v_mov_b32_e32 v5, v3
	v_pk_add_f32 v[2:3], v[10:11], v[4:5]
	v_pk_mul_f32 v[4:5], v[24:25], v[24:25]
	v_pk_mul_f32 v[10:11], v[22:23], v[22:23]
	v_pk_add_f32 v[2:3], v[2:3], v[2:3] op_sel:[0,1] op_sel_hi:[1,0]
	v_pk_mov_b32 v[12:13], v[10:11], v[4:5] op_sel:[1,0]
	v_mov_b32_e32 v11, v5
	v_pk_add_f32 v[4:5], v[12:13], v[10:11]
	v_mul_f32_e32 v10, v6, v6
	v_mul_f32_e32 v11, v7, v7
	v_pk_add_f32 v[4:5], v[4:5], v[4:5] op_sel:[0,1] op_sel_hi:[1,0]
	v_mov_b32_e32 v3, v10
	v_mov_b32_e32 v5, v11
	v_pk_add_f32 v[10:11], v[2:3], v[4:5]
	v_mul_f32_e32 v2, v15, v15
	v_pk_fma_f32 v[12:13], v[14:15], v[14:15], v[2:3] op_sel_hi:[1,1,0]
	v_mov_b32_e32 v13, v18
	v_mul_f32_e32 v18, v17, v17
	v_mul_f32_e32 v20, v9, v9
	v_pk_fma_f32 v[18:19], v[16:17], v[16:17], v[18:19] op_sel_hi:[1,1,0]
	s_ashr_i32 s9, s8, 31
	v_mov_b32_e32 v19, v20
	v_pk_add_f32 v[12:13], v[12:13], v[18:19]
	s_lshl_b64 s[8:9], s[8:9], 11
	v_pk_add_f32 v[10:11], v[10:11], v[12:13]
	s_nop 0
	v_add_f32_e32 v10, v10, v11
	s_nop 1
	v_add_f32_dpp v10, v10, v10 quad_perm:[1,0,3,2] row_mask:0xf bank_mask:0xf
	s_nop 1
	v_add_f32_dpp v10, v10, v10 quad_perm:[2,3,0,1] row_mask:0xf bank_mask:0xf
	s_nop 1
	v_add_f32_dpp v10, v10, v10 row_half_mirror row_mask:0xf bank_mask:0xf
	s_nop 1
	v_add_f32_dpp v10, v10, v10 row_mirror row_mask:0xf bank_mask:0xf
	v_mov_b32_e32 v11, v10
	s_nop 1
	v_permlane16_swap_b32 v11, v10
	v_add_f32_e32 v10, v10, v11
	v_mov_b32_e32 v11, v10
	s_nop 1
	v_permlane32_swap_b32 v11, v10
	v_add_f32_e32 v10, v10, v11
	v_fmamk_f32 v10, v10, 0x3a800000, v44
	v_mul_f32_e32 v11, 0x4f800000, v10
	v_cmp_gt_f32_e32 vcc, s15, v10
	s_nop 1
	v_cndmask_b32_e32 v10, v10, v11, vcc
	v_sqrt_f32_e32 v11, v10
	s_nop 0
	v_add_u32_e32 v12, -1, v11
	v_add_u32_e32 v13, 1, v11
	v_fma_f32 v18, -v12, v11, v10
	v_fma_f32 v19, -v13, v11, v10
	v_cmp_ge_f32_e64 s[0:1], 0, v18
	s_nop 1
	v_cndmask_b32_e64 v11, v11, v12, s[0:1]
	v_cmp_lt_f32_e64 s[0:1], 0, v19
	s_nop 1
	v_cndmask_b32_e64 v11, v11, v13, s[0:1]
	v_mul_f32_e32 v12, 0x37800000, v11
	v_cndmask_b32_e32 v11, v11, v12, vcc
	v_cmp_class_f32_e32 vcc, v10, v45
	s_nop 1
	v_cndmask_b32_e32 v12, v11, v10, vcc
	v_div_scale_f32 v13, s[0:1], v12, v12, 1.0
	v_rcp_f32_e32 v18, v13
	v_div_scale_f32 v19, vcc, 1.0, v12, 1.0
	v_lshl_add_u64 v[10:11], v[34:35], 0, s[8:9]
	v_fma_f32 v20, -v13, v18, 1.0
	v_fmac_f32_e32 v18, v20, v18
	v_mul_f32_e32 v20, v19, v18
	v_fma_f32 v21, -v13, v20, v19
	v_fmac_f32_e32 v20, v21, v18
	v_fma_f32 v13, -v13, v20, v19
	v_div_fmas_f32 v13, v13, v18, v20
	v_div_fixup_f32 v12, v13, v12, 1.0
	v_pk_mul_f32 v[18:19], v[30:31], v[12:13] op_sel_hi:[1,0]
	v_pk_mul_f32 v[20:21], v[32:33], v[12:13] op_sel_hi:[1,0]
	v_pk_mul_f32 v[2:3], v[64:65], v[18:19]
	v_pk_mul_f32 v[4:5], v[66:67], v[20:21]
	v_cvt_pk_bf16_f32 v2, v2, v3
	v_cvt_pk_bf16_f32 v3, v4, v5
	global_store_dwordx2 v[10:11], v[2:3], off
	v_pk_mul_f32 v[18:19], v[22:23], v[12:13] op_sel_hi:[1,0]
	v_pk_mul_f32 v[20:21], v[24:25], v[12:13] op_sel_hi:[1,0]
	v_pk_mul_f32 v[14:15], v[14:15], v[12:13] op_sel_hi:[1,0]
	v_pk_mul_f32 v[16:17], v[16:17], v[12:13] op_sel_hi:[1,0]
	v_pk_mul_f32 v[6:7], v[6:7], v[12:13] op_sel_hi:[1,0]
	v_pk_mul_f32 v[8:9], v[8:9], v[12:13] op_sel_hi:[1,0]
	v_pk_mul_f32 v[2:3], v[68:69], v[18:19]
	v_pk_mul_f32 v[4:5], v[70:71], v[20:21]
	v_cvt_pk_bf16_f32 v2, v2, v3
	v_cvt_pk_bf16_f32 v3, v4, v5
	global_store_dwordx2 v[10:11], v[2:3], off offset:512
	v_pk_mul_f32 v[2:3], v[72:73], v[14:15]
	v_pk_mul_f32 v[4:5], v[74:75], v[16:17]
	v_cvt_pk_bf16_f32 v2, v2, v3
	v_cvt_pk_bf16_f32 v3, v4, v5
	global_store_dwordx2 v[10:11], v[2:3], off offset:1024
	v_pk_mul_f32 v[2:3], v[76:77], v[6:7]
	v_pk_mul_f32 v[4:5], v[78:79], v[8:9]
	v_cvt_pk_bf16_f32 v2, v2, v3
	v_cvt_pk_bf16_f32 v3, v4, v5
	global_store_dwordx2 v[10:11], v[2:3], off offset:1536
	s_branch .LBB0_38

; __global__ void __launch_bounds__(NTHR, 2) hymba_fwd(Params P) {
;     ...
;         for (int t0 = gw; t0 < TT; t0 += 4 * NGW) {
;             u32x4 q[4][2][2]; int tt[4];
; #pragma unroll
;             for (int u = 0; u < 4; ++u) { const int t = t0 + u * NGW; tt[u] = t; const int tc = t < TT ? t : TT - 1;
; #pragma unroll
;                 for (int half = 0; half < 2; ++half) { const bf16_t* src = (half ? OSB : YSSD) + (size_t)tc * 1024;
; #pragma unroll
;                     for (int j = 0; j < 2; ++j) q[u][half][j] = __builtin_nontemporal_load((const u32x4*)src + lane + 64 * j); } }
; #pragma unroll
;             for (int u = 0; u < 4; ++u) { const int t = tt[u]; if (t >= TT) continue;
;                 bf16_t* orow = MIXIN + (size_t)t * MIXW;
; #pragma unroll
;                 for (int half = 0; half < 2; ++half) {
;                     const float* gg = half ? P.sb_norm_g : P.ssd_norm_g;
;                     float v[16]; float s = 0.f;
; #pragma unroll
;                     for (int j = 0; j < 2; ++j) { const u32x4 qq = q[u][half][j];
;                         v[8 * j + 0] = bflo(qq.x); v[8 * j + 1] = bfhi(qq.x); v[8 * j + 2] = bflo(qq.y); v[8 * j + 3] = bfhi(qq.y); v[8 * j + 4] = bflo(qq.z); v[8 * j + 5] = bfhi(qq.z); v[8 * j + 6] = bflo(qq.w); v[8 * j + 7] = bfhi(qq.w); }
; #pragma unroll
;                     for (int j = 0; j < 16; ++j) s += v[j] * v[j];
;                     const float rs = 1.f / sqrtf(wave_sum(s) * (1.f / 1024.f) + EPS);
; #pragma unroll
;                     for (int j = 0; j < 2; ++j) { const f32x4 ga = *(const f32x4*)(gg + 8 * lane + 512 * j), gb = *(const f32x4*)(gg + 8 * lane + 512 * j + 4); u32x4 w;
;                         w.x = pk2(v[8 * j + 0] * rs * ga.x, v[8 * j + 1] * rs * ga.y); w.y = pk2(v[8 * j + 2] * rs * ga.z, v[8 * j + 3] * rs * ga.w);
;                         w.z = pk2(v[8 * j + 4] * rs * gb.x, v[8 * j + 5] * rs * gb.y); w.w = pk2(v[8 * j + 6] * rs * gb.z, v[8 * j + 7] * rs * gb.w);
;                         *((u32x4*)(orow + half * 1024) + lane + 64 * j) = w; }
;                 }
;             }
;         }
.LBB0_622:
	s_ashr_i32 s3, s2, 31
	s_lshl_b64 s[0:1], s[2:3], 11
	v_lshl_add_u64 v[4:5], v[50:51], 0, s[0:1]
	global_load_dwordx4 v[0:3], v[4:5], off offset:1024 nt
	s_nop 0
	global_load_dwordx4 v[4:7], v[4:5], off nt
	s_nop 0
	s_add_i32 s10, s89, s2
	s_min_i32 s16, s10, 0x807f
	s_ashr_i32 s17, s16, 31
	s_add_i32 s8, s13, s2
	s_min_i32 s18, s8, 0x807f
	s_ashr_i32 s19, s18, 31
	s_add_i32 s6, s14, s2
	s_min_i32 s20, s6, 0x807f
	s_ashr_i32 s21, s20, 31
	s_lshl_b64 s[22:23], s[2:3], 12
	v_lshl_add_u64 v[58:59], v[48:49], 0, s[22:23]
	s_waitcnt vmcnt(1)
	v_lshlrev_b32_e32 v60, 16, v3
	s_waitcnt vmcnt(0)
	v_lshlrev_b32_e32 v92, 16, v4
	v_and_b32_e32 v93, 0xffff0000, v4
	v_lshlrev_b32_e32 v90, 16, v5
	v_and_b32_e32 v91, 0xffff0000, v5
	v_pk_mul_f32 v[8:9], v[92:93], v[92:93]
	v_lshlrev_b32_e32 v86, 16, v7
	v_and_b32_e32 v87, 0xffff0000, v7
	v_lshlrev_b32_e32 v88, 16, v6
	v_and_b32_e32 v89, 0xffff0000, v6
	v_pk_mul_f32 v[6:7], v[90:91], v[90:91]
	v_add_f32_e32 v8, v8, v9
	v_add_f32_e32 v6, v8, v6
	v_pk_mul_f32 v[4:5], v[88:89], v[88:89]
	v_add_f32_e32 v6, v6, v7
	v_add_f32_e32 v4, v6, v4
	v_and_b32_e32 v61, 0xffff0000, v3
	v_lshlrev_b32_e32 v94, 16, v2
	v_and_b32_e32 v95, 0xffff0000, v2
	v_pk_mul_f32 v[2:3], v[86:87], v[86:87]
	v_add_f32_e32 v4, v4, v5
	v_lshlrev_b32_e32 v98, 16, v0
	v_and_b32_e32 v99, 0xffff0000, v0
	v_add_f32_e32 v2, v4, v2
	v_pk_mul_f32 v[14:15], v[98:99], v[98:99]
	v_add_f32_e32 v2, v2, v3
	v_lshlrev_b32_e32 v96, 16, v1
	v_and_b32_e32 v97, 0xffff0000, v1
	v_add_f32_e32 v2, v2, v14
	v_pk_mul_f32 v[12:13], v[96:97], v[96:97]
	v_add_f32_e32 v2, v2, v15
	v_add_f32_e32 v2, v2, v12
	v_pk_mul_f32 v[10:11], v[94:95], v[94:95]
	v_add_f32_e32 v2, v2, v13
	v_add_f32_e32 v2, v2, v10
	v_pk_mul_f32 v[0:1], v[60:61], v[60:61]
	v_add_f32_e32 v2, v2, v11
	v_add_f32_e32 v0, v2, v0
	v_add_f32_e32 v0, v0, v1
	s_nop 1
	v_add_f32_dpp v2, v0, v0 quad_perm:[1,0,3,2] row_mask:0xf bank_mask:0xf
	v_lshl_add_u64 v[0:1], v[52:53], 0, s[0:1]
	s_lshl_b64 s[0:1], s[16:17], 11
	global_load_dwordx4 v[78:81], v[0:1], off offset:1024 nt
	global_load_dwordx4 v[82:85], v[0:1], off nt
	v_lshl_add_u64 v[0:1], v[50:51], 0, s[0:1]
	s_nop 1
	v_add_f32_dpp v2, v2, v2 quad_perm:[2,3,0,1] row_mask:0xf bank_mask:0xf
	global_load_dwordx4 v[44:47], v[0:1], off nt
	global_load_dwordx4 v[40:43], v[0:1], off offset:1024 nt
	s_lshl_b64 s[16:17], s[18:19], 11
	v_lshl_add_u64 v[4:5], v[50:51], 0, s[16:17]
	s_lshl_b64 s[18:19], s[20:21], 11
	s_nop 1
	v_add_f32_dpp v8, v2, v2 row_half_mirror row_mask:0xf bank_mask:0xf
	v_lshl_add_u64 v[2:3], v[52:53], 0, s[0:1]
	global_load_dwordx4 v[36:39], v[2:3], off nt
	global_load_dwordx4 v[32:35], v[2:3], off offset:1024 nt
	global_load_dwordx4 v[28:31], v[4:5], off nt
	global_load_dwordx4 v[24:27], v[4:5], off offset:1024 nt
	v_lshl_add_u64 v[6:7], v[52:53], 0, s[16:17]
	v_lshl_add_u64 v[100:101], v[52:53], 0, s[18:19]
	s_nop 1
	v_add_f32_dpp v10, v8, v8 row_mirror row_mask:0xf bank_mask:0xf
	v_lshl_add_u64 v[8:9], v[50:51], 0, s[18:19]
	s_cmp_gt_i32 s10, 0x807f
	v_mov_b32_e32 v11, v10
	v_mov_b32_e32 v0, v10
	s_nop 1
	v_permlane16_swap_b32 v11, v0
	v_add_f32_e32 v0, v0, v11
	global_load_dwordx4 v[20:23], v[6:7], off nt
	global_load_dwordx4 v[16:19], v[6:7], off offset:1024 nt
	global_load_dwordx4 v[12:15], v[8:9], off nt
	s_nop 0
	global_load_dwordx4 v[8:11], v[8:9], off offset:1024 nt
	v_mov_b32_e32 v1, v0
	s_nop 1
	v_permlane32_swap_b32 v1, v0
	v_add_f32_e32 v0, v0, v1
	v_fmamk_f32 v0, v0, 0x3a800000, v68
	v_mul_f32_e32 v1, 0x4f800000, v0
	v_cmp_gt_f32_e32 vcc, s15, v0
	s_nop 1
	v_cndmask_b32_e32 v0, v0, v1, vcc
	v_sqrt_f32_e32 v1, v0
	s_nop 0
	v_add_u32_e32 v2, -1, v1
	v_add_u32_e32 v3, 1, v1
	v_fma_f32 v4, -v2, v1, v0
	v_fma_f32 v5, -v3, v1, v0
	v_cmp_ge_f32_e64 s[0:1], 0, v4
	s_nop 1
	v_cndmask_b32_e64 v1, v1, v2, s[0:1]
	v_cmp_lt_f32_e64 s[0:1], 0, v5
	s_nop 1
	v_cndmask_b32_e64 v1, v1, v3, s[0:1]
	v_mul_f32_e32 v2, 0x37800000, v1
	v_cndmask_b32_e32 v1, v1, v2, vcc
	v_cmp_class_f32_e32 vcc, v0, v69
	s_nop 1
	v_cndmask_b32_e32 v102, v1, v0, vcc
	v_div_scale_f32 v103, s[0:1], v102, v102, 1.0
	v_rcp_f32_e32 v104, v103
	global_load_dwordx4 v[4:7], v[100:101], off nt
	global_load_dwordx4 v[0:3], v[100:101], off offset:1024 nt
	v_div_scale_f32 v100, vcc, 1.0, v102, 1.0
	v_fma_f32 v101, -v103, v104, 1.0
	v_fmac_f32_e32 v104, v101, v104
	v_mul_f32_e32 v101, v100, v104
	v_fma_f32 v105, -v103, v101, v100
	v_fmac_f32_e32 v101, v105, v104
	v_fma_f32 v100, -v103, v101, v100
	v_div_fmas_f32 v100, v100, v104, v101
	v_div_fixup_f32 v100, v100, v102, 1.0
	v_pk_mul_f32 v[92:93], v[100:101], v[92:93] op_sel_hi:[0,1]
	v_pk_mul_f32 v[90:91], v[100:101], v[90:91] op_sel_hi:[0,1]
	v_pk_mul_f32 v[88:89], v[100:101], v[88:89] op_sel_hi:[0,1]
	v_pk_mul_f32 v[86:87], v[100:101], v[86:87] op_sel_hi:[0,1]
	v_pk_mul_f32 v[74:75], v[92:93], v[120:121]
	v_pk_mul_f32 v[76:77], v[90:91], v[122:123]
	v_pk_mul_f32 v[88:89], v[88:89], v[124:125]
	v_pk_mul_f32 v[86:87], v[86:87], v[126:127]
	v_cvt_pk_bf16_f32 v70, v74, v75
	v_cvt_pk_bf16_f32 v71, v76, v77
	v_cvt_pk_bf16_f32 v72, v88, v89
	v_cvt_pk_bf16_f32 v73, v86, v87
	global_store_dwordx4 v[58:59], v[70:73], off
	s_nop 1
	s_nop 0
	s_waitcnt vmcnt(13)
; __device__ __forceinline__ float wave_sum(float v) {
; #pragma unroll
;     for (int o = 1; o < 64; o <<= 1) v += __shfl_xor(v, o);
;     return v;
; }
; __global__ void __launch_bounds__(NTHR, 2) hymba_fwd(Params P) {
;     ...
;                 for (int half = 0; half < 2; ++half) {
;                     const float* gg = half ? P.sb_norm_g : P.ssd_norm_g;
;                     float v[16]; float s = 0.f;
; #pragma unroll
;                     for (int j = 0; j < 2; ++j) { const u32x4 qq = q[u][half][j];
;                         v[8 * j + 0] = bflo(qq.x); v[8 * j + 1] = bfhi(qq.x); v[8 * j + 2] = bflo(qq.y); v[8 * j + 3] = bfhi(qq.y); v[8 * j + 4] = bflo(qq.z); v[8 * j + 5] = bfhi(qq.z); v[8 * j + 6] = bflo(qq.w); v[8 * j + 7] = bfhi(qq.w); }
; #pragma unroll
;                     for (int j = 0; j < 16; ++j) s += v[j] * v[j];
;                     const float rs = 1.f / sqrtf(wave_sum(s) * (1.f / 1024.f) + EPS);
; #pragma unroll
;                     for (int j = 0; j < 2; ++j) { const f32x4 ga = *(const f32x4*)(gg + 8 * lane + 512 * j), gb = *(const f32x4*)(gg + 8 * lane + 512 * j + 4); u32x4 w;
;                         w.x = pk2(v[8 * j + 0] * rs * ga.x, v[8 * j + 1] * rs * ga.y); w.y = pk2(v[8 * j + 2] * rs * ga.z, v[8 * j + 3] * rs * ga.w);
;                         w.z = pk2(v[8 * j + 4] * rs * gb.x, v[8 * j + 5] * rs * gb.y); w.w = pk2(v[8 * j + 6] * rs * gb.z, v[8 * j + 7] * rs * gb.w);
;                         *((u32x4*)(orow + half * 1024) + lane + 64 * j) = w; }
	v_lshlrev_b32_e32 v92, 16, v82
	v_and_b32_e32 v93, 0xffff0000, v82
	v_lshlrev_b32_e32 v88, 16, v85
	v_and_b32_e32 v89, 0xffff0000, v85
	v_lshlrev_b32_e32 v90, 16, v84
	v_and_b32_e32 v91, 0xffff0000, v84
	v_lshlrev_b32_e32 v84, 16, v83
	v_and_b32_e32 v85, 0xffff0000, v83
	v_pk_mul_f32 v[110:111], v[92:93], v[92:93]
	v_pk_mul_f32 v[108:109], v[84:85], v[84:85]
	v_add_f32_e32 v101, v110, v111
	v_add_f32_e32 v101, v101, v108
	v_pk_mul_f32 v[106:107], v[90:91], v[90:91]
	v_add_f32_e32 v101, v101, v109
	v_add_f32_e32 v101, v101, v106
	v_pk_mul_f32 v[104:105], v[88:89], v[88:89]
	v_add_f32_e32 v101, v101, v107
	v_lshlrev_b32_e32 v102, 16, v78
	v_and_b32_e32 v103, 0xffff0000, v78
	v_add_f32_e32 v101, v101, v104
	v_pk_mul_f32 v[116:117], v[102:103], v[102:103]
	v_add_f32_e32 v101, v101, v105
	v_lshlrev_b32_e32 v86, 16, v81
	v_and_b32_e32 v87, 0xffff0000, v81
	v_lshlrev_b32_e32 v82, 16, v80
	v_and_b32_e32 v83, 0xffff0000, v80
	v_lshlrev_b32_e32 v80, 16, v79
	v_and_b32_e32 v81, 0xffff0000, v79
	v_add_f32_e32 v101, v101, v116
	v_pk_mul_f32 v[114:115], v[80:81], v[80:81]
	v_add_f32_e32 v101, v101, v117
	v_add_f32_e32 v101, v101, v114
	v_add_f32_e32 v101, v101, v115
	v_pk_mul_f32 v[98:99], v[100:101], v[98:99] op_sel_hi:[0,1]
	v_pk_mul_f32 v[96:97], v[100:101], v[96:97] op_sel_hi:[0,1]
	v_pk_mul_f32 v[94:95], v[100:101], v[94:95] op_sel_hi:[0,1]
	v_pk_mul_f32 v[60:61], v[100:101], v[60:61] op_sel_hi:[0,1]
	v_pk_mul_f32 v[112:113], v[82:83], v[82:83]
	v_pk_mul_f32 v[78:79], v[86:87], v[86:87]
	v_pk_mul_f32 v[70:71], v[98:99], v[128:129]
	v_pk_mul_f32 v[72:73], v[96:97], v[130:131]
	v_pk_mul_f32 v[74:75], v[94:95], v[132:133]
	v_pk_mul_f32 v[60:61], v[60:61], v[134:135]
	v_cvt_pk_bf16_f32 v70, v70, v71
	v_cvt_pk_bf16_f32 v71, v72, v73
	v_cvt_pk_bf16_f32 v72, v74, v75
	v_cvt_pk_bf16_f32 v73, v60, v61
	global_store_dwordx4 v[58:59], v[70:73], off offset:1024
	s_nop 1
	s_nop 0
	v_add_f32_e32 v60, v101, v112
	v_add_f32_e32 v60, v60, v113
	v_add_f32_e32 v60, v60, v78
	v_add_f32_e32 v60, v60, v79
	s_nop 1
	v_add_f32_dpp v60, v60, v60 quad_perm:[1,0,3,2] row_mask:0xf bank_mask:0xf
	s_nop 1
	v_add_f32_dpp v60, v60, v60 quad_perm:[2,3,0,1] row_mask:0xf bank_mask:0xf
	s_nop 1
	v_add_f32_dpp v60, v60, v60 row_half_mirror row_mask:0xf bank_mask:0xf
	s_nop 1
	v_add_f32_dpp v60, v60, v60 row_mirror row_mask:0xf bank_mask:0xf
	v_mov_b32_e32 v61, v60
	s_nop 1
	v_permlane16_swap_b32 v61, v60
	v_add_f32_e32 v60, v60, v61
	v_mov_b32_e32 v61, v60
	s_nop 1
	v_permlane32_swap_b32 v61, v60
	v_add_f32_e32 v60, v60, v61
	v_fmamk_f32 v60, v60, 0x3a800000, v68
	v_mul_f32_e32 v61, 0x4f800000, v60
	v_cmp_gt_f32_e32 vcc, s15, v60
	s_nop 1
	v_cndmask_b32_e32 v60, v60, v61, vcc
	v_sqrt_f32_e32 v61, v60
	s_nop 0
	v_add_u32_e32 v78, -1, v61
	v_add_u32_e32 v79, 1, v61
	v_fma_f32 v94, -v78, v61, v60
	v_fma_f32 v95, -v79, v61, v60
	v_cmp_ge_f32_e64 s[0:1], 0, v94
	s_nop 1
	v_cndmask_b32_e64 v61, v61, v78, s[0:1]
	v_cmp_lt_f32_e64 s[0:1], 0, v95
	s_nop 1
	v_cndmask_b32_e64 v61, v61, v79, s[0:1]
	v_mul_f32_e32 v78, 0x37800000, v61
	v_cndmask_b32_e32 v61, v61, v78, vcc
	v_cmp_class_f32_e32 vcc, v60, v69
	s_nop 1
	v_cndmask_b32_e32 v60, v61, v60, vcc
	v_div_scale_f32 v61, s[0:1], v60, v60, 1.0
	v_rcp_f32_e32 v78, v61
	v_div_scale_f32 v79, vcc, 1.0, v60, 1.0
	v_fma_f32 v94, -v61, v78, 1.0
	v_fmac_f32_e32 v78, v94, v78
	v_mul_f32_e32 v94, v79, v78
	v_fma_f32 v95, -v61, v94, v79
	v_fmac_f32_e32 v94, v95, v78
	v_fma_f32 v61, -v61, v94, v79
	v_div_fmas_f32 v61, v61, v78, v94
	v_div_fixup_f32 v60, v61, v60, 1.0
	v_pk_mul_f32 v[78:79], v[60:61], v[92:93] op_sel_hi:[0,1]
	v_pk_mul_f32 v[84:85], v[60:61], v[84:85] op_sel_hi:[0,1]
	v_pk_mul_f32 v[90:91], v[60:61], v[90:91] op_sel_hi:[0,1]
	v_pk_mul_f32 v[88:89], v[60:61], v[88:89] op_sel_hi:[0,1]
	v_pk_mul_f32 v[74:75], v[78:79], v[136:137]
	v_pk_mul_f32 v[76:77], v[84:85], v[138:139]
	v_pk_mul_f32 v[78:79], v[90:91], v[140:141]
	v_pk_mul_f32 v[84:85], v[88:89], v[142:143]
	v_cvt_pk_bf16_f32 v70, v74, v75
	v_cvt_pk_bf16_f32 v71, v76, v77
	v_cvt_pk_bf16_f32 v72, v78, v79
	v_cvt_pk_bf16_f32 v73, v84, v85
	global_store_dwordx4 v[58:59], v[70:73], off offset:2048
	s_nop 1
	s_nop 0
	v_pk_mul_f32 v[78:79], v[60:61], v[102:103] op_sel_hi:[0,1]
	v_pk_mul_f32 v[80:81], v[60:61], v[80:81] op_sel_hi:[0,1]
	v_pk_mul_f32 v[82:83], v[60:61], v[82:83] op_sel_hi:[0,1]
	v_pk_mul_f32 v[60:61], v[60:61], v[86:87] op_sel_hi:[0,1]
	v_pk_mul_f32 v[70:71], v[78:79], v[144:145]
	v_pk_mul_f32 v[72:73], v[80:81], v[146:147]
	v_pk_mul_f32 v[74:75], v[82:83], v[148:149]
	v_pk_mul_f32 v[60:61], v[60:61], v[150:151]
	v_cvt_pk_bf16_f32 v70, v70, v71
	v_cvt_pk_bf16_f32 v71, v72, v73
	v_cvt_pk_bf16_f32 v72, v74, v75
	v_cvt_pk_bf16_f32 v73, v60, v61
	global_store_dwordx4 v[58:59], v[70:73], off offset:3072
	s_nop 1
	s_cbranch_scc1 .LBB0_625
; __device__ __forceinline__ float wave_sum(float v) {
; #pragma unroll
;     for (int o = 1; o < 64; o <<= 1) v += __shfl_xor(v, o);
;     return v;
; }
; __global__ void __launch_bounds__(NTHR, 2) hymba_fwd(Params P) {
;     ...
;                 for (int half = 0; half < 2; ++half) {
;                     const float* gg = half ? P.sb_norm_g : P.ssd_norm_g;
;                     float v[16]; float s = 0.f;
; #pragma unroll
;                     for (int j = 0; j < 2; ++j) { const u32x4 qq = q[u][half][j];
;                         v[8 * j + 0] = bflo(qq.x); v[8 * j + 1] = bfhi(qq.x); v[8 * j + 2] = bflo(qq.y); v[8 * j + 3] = bfhi(qq.y); v[8 * j + 4] = bflo(qq.z); v[8 * j + 5] = bfhi(qq.z); v[8 * j + 6] = bflo(qq.w); v[8 * j + 7] = bfhi(qq.w); }
; #pragma unroll
;                     for (int j = 0; j < 16; ++j) s += v[j] * v[j];
;                     const float rs = 1.f / sqrtf(wave_sum(s) * (1.f / 1024.f) + EPS);
; #pragma unroll
;                     for (int j = 0; j < 2; ++j) { const f32x4 ga = *(const f32x4*)(gg + 8 * lane + 512 * j), gb = *(const f32x4*)(gg + 8 * lane + 512 * j + 4); u32x4 w;
;                         w.x = pk2(v[8 * j + 0] * rs * ga.x, v[8 * j + 1] * rs * ga.y); w.y = pk2(v[8 * j + 2] * rs * ga.z, v[8 * j + 3] * rs * ga.w);
;                         w.z = pk2(v[8 * j + 4] * rs * gb.x, v[8 * j + 5] * rs * gb.y); w.w = pk2(v[8 * j + 6] * rs * gb.z, v[8 * j + 7] * rs * gb.w);
;                         *((u32x4*)(orow + half * 1024) + lane + 64 * j) = w; }
	s_waitcnt vmcnt(12)
	v_lshlrev_b32_e32 v88, 16, v44
	v_and_b32_e32 v89, 0xffff0000, v44
	v_lshlrev_b32_e32 v84, 16, v45
	v_and_b32_e32 v85, 0xffff0000, v45
	v_pk_mul_f32 v[44:45], v[88:89], v[88:89]
	v_pk_mul_f32 v[86:87], v[84:85], v[84:85]
	v_add_f32_e32 v44, v44, v45
	v_lshlrev_b32_e32 v82, 16, v46
	v_and_b32_e32 v83, 0xffff0000, v46
	v_add_f32_e32 v44, v44, v86
	v_lshlrev_b32_e32 v78, 16, v47
	v_and_b32_e32 v79, 0xffff0000, v47
	v_pk_mul_f32 v[46:47], v[82:83], v[82:83]
	v_add_f32_e32 v44, v44, v87
	v_add_f32_e32 v44, v44, v46
	v_pk_mul_f32 v[80:81], v[78:79], v[78:79]
	v_add_f32_e32 v44, v44, v47
	v_lshlrev_b32_e32 v96, 16, v40
	v_and_b32_e32 v97, 0xffff0000, v40
	v_add_f32_e32 v44, v44, v80
	v_lshlrev_b32_e32 v92, 16, v41
	v_and_b32_e32 v93, 0xffff0000, v41
	v_pk_mul_f32 v[40:41], v[96:97], v[96:97]
	v_add_f32_e32 v44, v44, v81
	v_add_f32_e32 v40, v44, v40
	v_pk_mul_f32 v[94:95], v[92:93], v[92:93]
	v_add_f32_e32 v40, v40, v41
	v_lshlrev_b32_e32 v90, 16, v42
	v_and_b32_e32 v91, 0xffff0000, v42
	v_add_f32_e32 v40, v40, v94
	v_lshlrev_b32_e32 v74, 16, v43
	v_and_b32_e32 v75, 0xffff0000, v43
	v_pk_mul_f32 v[42:43], v[90:91], v[90:91]
	v_add_f32_e32 v40, v40, v95
	v_add_f32_e32 v40, v40, v42
	v_pk_mul_f32 v[76:77], v[74:75], v[74:75]
	v_add_f32_e32 v40, v40, v43
	v_add_f32_e32 v40, v40, v76
	v_add_f32_e32 v40, v40, v77
	s_ashr_i32 s11, s10, 31
	v_lshlrev_b32_e32 v86, 16, v32
	v_and_b32_e32 v87, 0xffff0000, v32
	v_pk_mul_f32 v[100:101], v[86:87], v[86:87]
	s_nop 1
	v_add_f32_dpp v40, v40, v40 quad_perm:[1,0,3,2] row_mask:0xf bank_mask:0xf
	s_nop 1
	v_add_f32_dpp v40, v40, v40 quad_perm:[2,3,0,1] row_mask:0xf bank_mask:0xf
	s_nop 1
	v_add_f32_dpp v40, v40, v40 row_half_mirror row_mask:0xf bank_mask:0xf
	s_nop 1
	v_add_f32_dpp v40, v40, v40 row_mirror row_mask:0xf bank_mask:0xf
	v_mov_b32_e32 v41, v40
	s_nop 1
	v_permlane16_swap_b32 v41, v40
	v_add_f32_e32 v40, v40, v41
	v_mov_b32_e32 v41, v40
	s_nop 1
	v_permlane32_swap_b32 v41, v40
	v_add_f32_e32 v40, v40, v41
	v_fmamk_f32 v40, v40, 0x3a800000, v68
	v_mul_f32_e32 v41, 0x4f800000, v40
	v_cmp_gt_f32_e32 vcc, s15, v40
	s_nop 1
	v_cndmask_b32_e32 v40, v40, v41, vcc
	v_sqrt_f32_e32 v41, v40
	s_nop 0
	v_add_u32_e32 v42, -1, v41
	v_fma_f32 v44, -v42, v41, v40
	v_add_u32_e32 v43, 1, v41
	v_cmp_ge_f32_e64 s[0:1], 0, v44
	s_nop 1
	v_cndmask_b32_e64 v42, v41, v42, s[0:1]
	v_fma_f32 v41, -v43, v41, v40
	v_cmp_lt_f32_e64 s[0:1], 0, v41
	s_nop 1
	v_cndmask_b32_e64 v41, v42, v43, s[0:1]
	v_mul_f32_e32 v42, 0x37800000, v41
	v_cndmask_b32_e32 v41, v41, v42, vcc
	v_cmp_class_f32_e32 vcc, v40, v69
	s_nop 1
	v_cndmask_b32_e32 v40, v41, v40, vcc
	v_div_scale_f32 v41, s[0:1], v40, v40, 1.0
	v_rcp_f32_e32 v42, v41
	s_lshl_b64 s[0:1], s[10:11], 12
	v_lshl_add_u64 v[76:77], v[48:49], 0, s[0:1]
	v_fma_f32 v43, -v41, v42, 1.0
	v_fmac_f32_e32 v42, v43, v42
	v_div_scale_f32 v43, vcc, 1.0, v40, 1.0
	v_mul_f32_e32 v44, v43, v42
	v_fma_f32 v45, -v41, v44, v43
	v_fmac_f32_e32 v44, v45, v42
	v_fma_f32 v41, -v41, v44, v43
	v_div_fmas_f32 v41, v41, v42, v44
	v_div_fixup_f32 v80, v41, v40, 1.0
	v_pk_mul_f32 v[40:41], v[80:81], v[88:89] op_sel_hi:[0,1]
	v_pk_mul_f32 v[42:43], v[80:81], v[84:85] op_sel_hi:[0,1]
	v_pk_mul_f32 v[40:41], v[40:41], v[120:121]
	v_pk_mul_f32 v[42:43], v[42:43], v[122:123]
	v_cvt_pk_bf16_f32 v40, v40, v41
	v_cvt_pk_bf16_f32 v41, v42, v43
	v_pk_mul_f32 v[42:43], v[80:81], v[82:83] op_sel_hi:[0,1]
	v_pk_mul_f32 v[44:45], v[80:81], v[78:79] op_sel_hi:[0,1]
	v_pk_mul_f32 v[42:43], v[42:43], v[124:125]
	v_pk_mul_f32 v[44:45], v[44:45], v[126:127]
	v_cvt_pk_bf16_f32 v42, v42, v43
	v_cvt_pk_bf16_f32 v43, v44, v45
	global_store_dwordx4 v[76:77], v[40:43], off
	s_nop 1
	s_nop 0
	v_lshlrev_b32_e32 v78, 16, v36
	v_and_b32_e32 v79, 0xffff0000, v36
	v_lshlrev_b32_e32 v60, 16, v39
	v_and_b32_e32 v61, 0xffff0000, v39
	v_lshlrev_b32_e32 v70, 16, v38
	v_and_b32_e32 v71, 0xffff0000, v38
	v_lshlrev_b32_e32 v72, 16, v37
	v_and_b32_e32 v73, 0xffff0000, v37
	v_pk_mul_f32 v[38:39], v[78:79], v[78:79]
	v_pk_mul_f32 v[36:37], v[72:73], v[72:73]
	v_add_f32_e32 v38, v38, v39
	v_add_f32_e32 v36, v38, v36
	v_lshlrev_b32_e32 v58, 16, v35
	v_and_b32_e32 v59, 0xffff0000, v35
; __device__ __forceinline__ float wave_sum(float v) {
; #pragma unroll
;     for (int o = 1; o < 64; o <<= 1) v += __shfl_xor(v, o);
;     return v;
; }
; __global__ void __launch_bounds__(NTHR, 2) hymba_fwd(Params P) {
;     ...
;                 for (int half = 0; half < 2; ++half) {
;                     const float* gg = half ? P.sb_norm_g : P.ssd_norm_g;
;                     float v[16]; float s = 0.f;
; #pragma unroll
;                     for (int j = 0; j < 2; ++j) { const u32x4 qq = q[u][half][j];
;                         v[8 * j + 0] = bflo(qq.x); v[8 * j + 1] = bfhi(qq.x); v[8 * j + 2] = bflo(qq.y); v[8 * j + 3] = bfhi(qq.y); v[8 * j + 4] = bflo(qq.z); v[8 * j + 5] = bfhi(qq.z); v[8 * j + 6] = bflo(qq.w); v[8 * j + 7] = bfhi(qq.w); }
; #pragma unroll
;                     for (int j = 0; j < 16; ++j) s += v[j] * v[j];
;                     const float rs = 1.f / sqrtf(wave_sum(s) * (1.f / 1024.f) + EPS);
; #pragma unroll
;                     for (int j = 0; j < 2; ++j) { const f32x4 ga = *(const f32x4*)(gg + 8 * lane + 512 * j), gb = *(const f32x4*)(gg + 8 * lane + 512 * j + 4); u32x4 w;
;                         w.x = pk2(v[8 * j + 0] * rs * ga.x, v[8 * j + 1] * rs * ga.y); w.y = pk2(v[8 * j + 2] * rs * ga.z, v[8 * j + 3] * rs * ga.w);
;                         w.z = pk2(v[8 * j + 4] * rs * gb.x, v[8 * j + 5] * rs * gb.y); w.w = pk2(v[8 * j + 6] * rs * gb.z, v[8 * j + 7] * rs * gb.w);
;                         *((u32x4*)(orow + half * 1024) + lane + 64 * j) = w; }
	v_lshlrev_b32_e32 v82, 16, v34
	v_and_b32_e32 v83, 0xffff0000, v34
	v_pk_mul_f32 v[34:35], v[70:71], v[70:71]
	v_add_f32_e32 v36, v36, v37
	v_add_f32_e32 v34, v36, v34
	v_lshlrev_b32_e32 v84, 16, v33
	v_and_b32_e32 v85, 0xffff0000, v33
	v_pk_mul_f32 v[32:33], v[60:61], v[60:61]
	v_add_f32_e32 v34, v34, v35
	v_add_f32_e32 v32, v34, v32
	v_add_f32_e32 v32, v32, v33
	v_add_f32_e32 v32, v32, v100
	v_pk_mul_f32 v[98:99], v[84:85], v[84:85]
	v_add_f32_e32 v32, v32, v101
	v_add_f32_e32 v32, v32, v98
	v_add_f32_e32 v81, v32, v99
	v_pk_mul_f32 v[32:33], v[80:81], v[96:97] op_sel_hi:[0,1]
	v_pk_mul_f32 v[34:35], v[80:81], v[92:93] op_sel_hi:[0,1]
	v_pk_mul_f32 v[36:37], v[80:81], v[90:91] op_sel_hi:[0,1]
	v_pk_mul_f32 v[38:39], v[80:81], v[74:75] op_sel_hi:[0,1]
	v_pk_mul_f32 v[94:95], v[82:83], v[82:83]
	v_pk_mul_f32 v[88:89], v[58:59], v[58:59]
	v_pk_mul_f32 v[32:33], v[32:33], v[128:129]
	v_pk_mul_f32 v[34:35], v[34:35], v[130:131]
	v_pk_mul_f32 v[36:37], v[36:37], v[132:133]
	v_pk_mul_f32 v[38:39], v[38:39], v[134:135]
	v_cvt_pk_bf16_f32 v32, v32, v33
	v_cvt_pk_bf16_f32 v33, v34, v35
	v_cvt_pk_bf16_f32 v34, v36, v37
	v_cvt_pk_bf16_f32 v35, v38, v39
	global_store_dwordx4 v[76:77], v[32:35], off offset:1024
	s_nop 1
	s_nop 0
	v_add_f32_e32 v40, v81, v94
	v_add_f32_e32 v40, v40, v95
	v_add_f32_e32 v40, v40, v88
	v_add_f32_e32 v40, v40, v89
	s_nop 1
	v_add_f32_dpp v40, v40, v40 quad_perm:[1,0,3,2] row_mask:0xf bank_mask:0xf
	s_nop 1
	v_add_f32_dpp v40, v40, v40 quad_perm:[2,3,0,1] row_mask:0xf bank_mask:0xf
	s_nop 1
	v_add_f32_dpp v40, v40, v40 row_half_mirror row_mask:0xf bank_mask:0xf
	s_nop 1
	v_add_f32_dpp v40, v40, v40 row_mirror row_mask:0xf bank_mask:0xf
	v_mov_b32_e32 v41, v40
	s_nop 1
	v_permlane16_swap_b32 v41, v40
	v_add_f32_e32 v40, v40, v41
	v_mov_b32_e32 v41, v40
	s_nop 1
	v_permlane32_swap_b32 v41, v40
	v_add_f32_e32 v40, v40, v41
	v_fmamk_f32 v40, v40, 0x3a800000, v68
	v_mul_f32_e32 v41, 0x4f800000, v40
	v_cmp_gt_f32_e32 vcc, s15, v40
	s_nop 1
	v_cndmask_b32_e32 v40, v40, v41, vcc
	v_sqrt_f32_e32 v41, v40
	s_nop 0
	v_add_u32_e32 v42, -1, v41
	v_add_u32_e32 v43, 1, v41
	v_fma_f32 v44, -v42, v41, v40
	v_fma_f32 v45, -v43, v41, v40
	v_cmp_ge_f32_e64 s[0:1], 0, v44
	s_nop 1
	v_cndmask_b32_e64 v41, v41, v42, s[0:1]
	v_cmp_lt_f32_e64 s[0:1], 0, v45
	s_nop 1
	v_cndmask_b32_e64 v41, v41, v43, s[0:1]
	v_mul_f32_e32 v42, 0x37800000, v41
	v_cndmask_b32_e32 v41, v41, v42, vcc
	v_cmp_class_f32_e32 vcc, v40, v69
	s_nop 1
	v_cndmask_b32_e32 v40, v41, v40, vcc
	v_div_scale_f32 v41, s[0:1], v40, v40, 1.0
	v_rcp_f32_e32 v42, v41
	v_div_scale_f32 v43, vcc, 1.0, v40, 1.0
	v_fma_f32 v44, -v41, v42, 1.0
	v_fmac_f32_e32 v42, v44, v42
	v_mul_f32_e32 v44, v43, v42
	v_fma_f32 v45, -v41, v44, v43
	v_fmac_f32_e32 v44, v45, v42
	v_fma_f32 v41, -v41, v44, v43
	v_div_fmas_f32 v41, v41, v42, v44
	v_div_fixup_f32 v40, v41, v40, 1.0
	v_pk_mul_f32 v[42:43], v[40:41], v[78:79] op_sel_hi:[0,1]
	v_pk_mul_f32 v[44:45], v[40:41], v[72:73] op_sel_hi:[0,1]
	v_pk_mul_f32 v[46:47], v[40:41], v[70:71] op_sel_hi:[0,1]
	v_pk_mul_f32 v[60:61], v[40:41], v[60:61] op_sel_hi:[0,1]
	v_pk_mul_f32 v[36:37], v[42:43], v[136:137]
	v_pk_mul_f32 v[38:39], v[44:45], v[138:139]
	v_pk_mul_f32 v[42:43], v[46:47], v[140:141]
	v_pk_mul_f32 v[44:45], v[60:61], v[142:143]
	v_cvt_pk_bf16_f32 v32, v36, v37
	v_cvt_pk_bf16_f32 v33, v38, v39
	v_cvt_pk_bf16_f32 v34, v42, v43
	v_cvt_pk_bf16_f32 v35, v44, v45
	global_store_dwordx4 v[76:77], v[32:35], off offset:2048
	s_nop 1
	s_nop 0
	v_pk_mul_f32 v[42:43], v[40:41], v[86:87] op_sel_hi:[0,1]
	v_pk_mul_f32 v[44:45], v[40:41], v[84:85] op_sel_hi:[0,1]
	v_pk_mul_f32 v[46:47], v[40:41], v[82:83] op_sel_hi:[0,1]
	v_pk_mul_f32 v[40:41], v[40:41], v[58:59] op_sel_hi:[0,1]
	v_pk_mul_f32 v[32:33], v[42:43], v[144:145]
	v_pk_mul_f32 v[34:35], v[44:45], v[146:147]
	v_pk_mul_f32 v[36:37], v[46:47], v[148:149]
	v_pk_mul_f32 v[38:39], v[40:41], v[150:151]
	v_cvt_pk_bf16_f32 v32, v32, v33
	v_cvt_pk_bf16_f32 v33, v34, v35
	v_cvt_pk_bf16_f32 v34, v36, v37
	v_cvt_pk_bf16_f32 v35, v38, v39
	global_store_dwordx4 v[76:77], v[32:35], off offset:3072
	s_nop 1
	s_cmp_gt_i32 s8, 0x807f
	s_cbranch_scc0 .LBB0_626

; __device__ __forceinline__ float wave_sum(float v) {
; #pragma unroll
;     for (int o = 1; o < 64; o <<= 1) v += __shfl_xor(v, o);
;     return v;
; }
; __global__ void __launch_bounds__(NTHR, 2) hymba_fwd(Params P) {
;     ...
;                 for (int half = 0; half < 2; ++half) {
;                     const float* gg = half ? P.sb_norm_g : P.ssd_norm_g;
;                     float v[16]; float s = 0.f;
; #pragma unroll
;                     for (int j = 0; j < 2; ++j) { const u32x4 qq = q[u][half][j];
;                         v[8 * j + 0] = bflo(qq.x); v[8 * j + 1] = bfhi(qq.x); v[8 * j + 2] = bflo(qq.y); v[8 * j + 3] = bfhi(qq.y); v[8 * j + 4] = bflo(qq.z); v[8 * j + 5] = bfhi(qq.z); v[8 * j + 6] = bflo(qq.w); v[8 * j + 7] = bfhi(qq.w); }
; #pragma unroll
;                     for (int j = 0; j < 16; ++j) s += v[j] * v[j];
;                     const float rs = 1.f / sqrtf(wave_sum(s) * (1.f / 1024.f) + EPS);
; #pragma unroll
;                     for (int j = 0; j < 2; ++j) { const f32x4 ga = *(const f32x4*)(gg + 8 * lane + 512 * j), gb = *(const f32x4*)(gg + 8 * lane + 512 * j + 4); u32x4 w;
;                         w.x = pk2(v[8 * j + 0] * rs * ga.x, v[8 * j + 1] * rs * ga.y); w.y = pk2(v[8 * j + 2] * rs * ga.z, v[8 * j + 3] * rs * ga.w);
;                         w.z = pk2(v[8 * j + 4] * rs * gb.x, v[8 * j + 5] * rs * gb.y); w.w = pk2(v[8 * j + 6] * rs * gb.z, v[8 * j + 7] * rs * gb.w);
;                         *((u32x4*)(orow + half * 1024) + lane + 64 * j) = w; }
.LBB0_626:
	s_waitcnt vmcnt(8)
	v_lshlrev_b32_e32 v72, 16, v28
	v_and_b32_e32 v73, 0xffff0000, v28
	v_lshlrev_b32_e32 v60, 16, v29
	v_and_b32_e32 v61, 0xffff0000, v29
	v_pk_mul_f32 v[28:29], v[72:73], v[72:73]
	v_pk_mul_f32 v[70:71], v[60:61], v[60:61]
	v_add_f32_e32 v28, v28, v29
	v_lshlrev_b32_e32 v58, 16, v30
	v_and_b32_e32 v59, 0xffff0000, v30
	v_add_f32_e32 v28, v28, v70
	v_lshlrev_b32_e32 v44, 16, v31
	v_and_b32_e32 v45, 0xffff0000, v31
	v_pk_mul_f32 v[30:31], v[58:59], v[58:59]
	v_add_f32_e32 v28, v28, v71
	v_add_f32_e32 v28, v28, v30
	v_pk_mul_f32 v[46:47], v[44:45], v[44:45]
	v_add_f32_e32 v28, v28, v31
	v_lshlrev_b32_e32 v80, 16, v24
	v_and_b32_e32 v81, 0xffff0000, v24
	v_add_f32_e32 v28, v28, v46
	v_lshlrev_b32_e32 v76, 16, v25
	v_and_b32_e32 v77, 0xffff0000, v25
	v_pk_mul_f32 v[24:25], v[80:81], v[80:81]
	v_add_f32_e32 v28, v28, v47
	v_add_f32_e32 v24, v28, v24
	v_pk_mul_f32 v[78:79], v[76:77], v[76:77]
	v_add_f32_e32 v24, v24, v25
	v_lshlrev_b32_e32 v74, 16, v26
	v_and_b32_e32 v75, 0xffff0000, v26
	v_add_f32_e32 v24, v24, v78
	v_lshlrev_b32_e32 v40, 16, v27
	v_and_b32_e32 v41, 0xffff0000, v27
	v_pk_mul_f32 v[26:27], v[74:75], v[74:75]
	v_add_f32_e32 v24, v24, v79
	v_add_f32_e32 v24, v24, v26
	v_pk_mul_f32 v[42:43], v[40:41], v[40:41]
	v_add_f32_e32 v24, v24, v27
	v_add_f32_e32 v24, v24, v42
	v_add_f32_e32 v24, v24, v43
	s_ashr_i32 s9, s8, 31
	v_lshlrev_b32_e32 v70, 16, v16
	v_and_b32_e32 v71, 0xffff0000, v16
	v_pk_mul_f32 v[84:85], v[70:71], v[70:71]
	s_nop 1
	v_add_f32_dpp v24, v24, v24 quad_perm:[1,0,3,2] row_mask:0xf bank_mask:0xf
	s_nop 1
	v_add_f32_dpp v24, v24, v24 quad_perm:[2,3,0,1] row_mask:0xf bank_mask:0xf
	s_nop 1
	v_add_f32_dpp v24, v24, v24 row_half_mirror row_mask:0xf bank_mask:0xf
	s_nop 1
	v_add_f32_dpp v24, v24, v24 row_mirror row_mask:0xf bank_mask:0xf
	v_mov_b32_e32 v25, v24
	s_nop 1
	v_permlane16_swap_b32 v25, v24
	v_add_f32_e32 v24, v24, v25
	v_mov_b32_e32 v25, v24
	s_nop 1
	v_permlane32_swap_b32 v25, v24
	v_add_f32_e32 v24, v24, v25
	v_fmamk_f32 v24, v24, 0x3a800000, v68
	v_mul_f32_e32 v25, 0x4f800000, v24
	v_cmp_gt_f32_e32 vcc, s15, v24
	s_nop 1
	v_cndmask_b32_e32 v24, v24, v25, vcc
	v_sqrt_f32_e32 v25, v24
	s_nop 0
	v_add_u32_e32 v26, -1, v25
	v_fma_f32 v28, -v26, v25, v24
	v_add_u32_e32 v27, 1, v25
	v_cmp_ge_f32_e64 s[0:1], 0, v28
	s_nop 1
	v_cndmask_b32_e64 v26, v25, v26, s[0:1]
	v_fma_f32 v25, -v27, v25, v24
	v_cmp_lt_f32_e64 s[0:1], 0, v25
	s_nop 1
	v_cndmask_b32_e64 v25, v26, v27, s[0:1]
	v_mul_f32_e32 v26, 0x37800000, v25
	v_cndmask_b32_e32 v25, v25, v26, vcc
	v_cmp_class_f32_e32 vcc, v24, v69
	s_nop 1
	v_cndmask_b32_e32 v24, v25, v24, vcc
	v_div_scale_f32 v25, s[0:1], v24, v24, 1.0
	v_rcp_f32_e32 v26, v25
	s_lshl_b64 s[0:1], s[8:9], 12
	v_lshl_add_u64 v[42:43], v[48:49], 0, s[0:1]
	v_fma_f32 v27, -v25, v26, 1.0
	v_fmac_f32_e32 v26, v27, v26
	v_div_scale_f32 v27, vcc, 1.0, v24, 1.0
	v_mul_f32_e32 v28, v27, v26
	v_fma_f32 v29, -v25, v28, v27
	v_fmac_f32_e32 v28, v29, v26
	v_fma_f32 v25, -v25, v28, v27
	v_div_fmas_f32 v25, v25, v26, v28
	v_div_fixup_f32 v46, v25, v24, 1.0
	v_pk_mul_f32 v[24:25], v[46:47], v[72:73] op_sel_hi:[0,1]
	v_pk_mul_f32 v[26:27], v[46:47], v[60:61] op_sel_hi:[0,1]
	v_pk_mul_f32 v[24:25], v[24:25], v[120:121]
	v_pk_mul_f32 v[26:27], v[26:27], v[122:123]
	v_cvt_pk_bf16_f32 v24, v24, v25
	v_cvt_pk_bf16_f32 v25, v26, v27
	v_pk_mul_f32 v[26:27], v[46:47], v[58:59] op_sel_hi:[0,1]
	v_pk_mul_f32 v[28:29], v[46:47], v[44:45] op_sel_hi:[0,1]
	v_pk_mul_f32 v[26:27], v[26:27], v[124:125]
	v_pk_mul_f32 v[28:29], v[28:29], v[126:127]
	v_cvt_pk_bf16_f32 v26, v26, v27
	v_cvt_pk_bf16_f32 v27, v28, v29
	global_store_dwordx4 v[42:43], v[24:27], off
	s_nop 1
	s_nop 0
	v_lshlrev_b32_e32 v44, 16, v20
	v_and_b32_e32 v45, 0xffff0000, v20
	v_lshlrev_b32_e32 v34, 16, v23
	v_and_b32_e32 v35, 0xffff0000, v23
	v_lshlrev_b32_e32 v36, 16, v22
	v_and_b32_e32 v37, 0xffff0000, v22
	v_lshlrev_b32_e32 v38, 16, v21
	v_and_b32_e32 v39, 0xffff0000, v21
	v_pk_mul_f32 v[22:23], v[44:45], v[44:45]
	v_pk_mul_f32 v[20:21], v[38:39], v[38:39]
	v_add_f32_e32 v22, v22, v23
	v_add_f32_e32 v20, v22, v20
	v_lshlrev_b32_e32 v32, 16, v19
	v_and_b32_e32 v33, 0xffff0000, v19
	v_lshlrev_b32_e32 v58, 16, v18
	v_and_b32_e32 v59, 0xffff0000, v18
	v_pk_mul_f32 v[18:19], v[36:37], v[36:37]
	v_add_f32_e32 v20, v20, v21
	v_add_f32_e32 v18, v20, v18
	v_lshlrev_b32_e32 v60, 16, v17
	v_and_b32_e32 v61, 0xffff0000, v17
	v_pk_mul_f32 v[16:17], v[34:35], v[34:35]
	v_add_f32_e32 v18, v18, v19
	v_add_f32_e32 v16, v18, v16
	v_add_f32_e32 v16, v16, v17
	v_add_f32_e32 v16, v16, v84
	v_pk_mul_f32 v[82:83], v[60:61], v[60:61]
	v_add_f32_e32 v16, v16, v85
	v_add_f32_e32 v16, v16, v82
	v_add_f32_e32 v47, v16, v83
	v_pk_mul_f32 v[16:17], v[46:47], v[80:81] op_sel_hi:[0,1]
	v_pk_mul_f32 v[18:19], v[46:47], v[76:77] op_sel_hi:[0,1]
	v_pk_mul_f32 v[20:21], v[46:47], v[74:75] op_sel_hi:[0,1]
	v_pk_mul_f32 v[22:23], v[46:47], v[40:41] op_sel_hi:[0,1]
	v_pk_mul_f32 v[78:79], v[58:59], v[58:59]
	v_pk_mul_f32 v[72:73], v[32:33], v[32:33]
	v_pk_mul_f32 v[16:17], v[16:17], v[128:129]
	v_pk_mul_f32 v[18:19], v[18:19], v[130:131]
	v_pk_mul_f32 v[20:21], v[20:21], v[132:133]
	v_pk_mul_f32 v[22:23], v[22:23], v[134:135]
	v_cvt_pk_bf16_f32 v16, v16, v17
	v_cvt_pk_bf16_f32 v17, v18, v19
	v_cvt_pk_bf16_f32 v18, v20, v21
	v_cvt_pk_bf16_f32 v19, v22, v23
	global_store_dwordx4 v[42:43], v[16:19], off offset:1024
	s_nop 1
	s_nop 0
	v_add_f32_e32 v24, v47, v78
	v_add_f32_e32 v24, v24, v79
	v_add_f32_e32 v24, v24, v72
	v_add_f32_e32 v24, v24, v73
	s_nop 1
	v_add_f32_dpp v24, v24, v24 quad_perm:[1,0,3,2] row_mask:0xf bank_mask:0xf
	s_nop 1
; __device__ __forceinline__ float wave_sum(float v) {
; #pragma unroll
;     for (int o = 1; o < 64; o <<= 1) v += __shfl_xor(v, o);
;     return v;
; }
; __global__ void __launch_bounds__(NTHR, 2) hymba_fwd(Params P) {
;     ...
;                 for (int half = 0; half < 2; ++half) {
;                     const float* gg = half ? P.sb_norm_g : P.ssd_norm_g;
;                     float v[16]; float s = 0.f;
; #pragma unroll
;                     for (int j = 0; j < 2; ++j) { const u32x4 qq = q[u][half][j];
;                         v[8 * j + 0] = bflo(qq.x); v[8 * j + 1] = bfhi(qq.x); v[8 * j + 2] = bflo(qq.y); v[8 * j + 3] = bfhi(qq.y); v[8 * j + 4] = bflo(qq.z); v[8 * j + 5] = bfhi(qq.z); v[8 * j + 6] = bflo(qq.w); v[8 * j + 7] = bfhi(qq.w); }
; #pragma unroll
;                     for (int j = 0; j < 16; ++j) s += v[j] * v[j];
;                     const float rs = 1.f / sqrtf(wave_sum(s) * (1.f / 1024.f) + EPS);
; #pragma unroll
;                     for (int j = 0; j < 2; ++j) { const f32x4 ga = *(const f32x4*)(gg + 8 * lane + 512 * j), gb = *(const f32x4*)(gg + 8 * lane + 512 * j + 4); u32x4 w;
;                         w.x = pk2(v[8 * j + 0] * rs * ga.x, v[8 * j + 1] * rs * ga.y); w.y = pk2(v[8 * j + 2] * rs * ga.z, v[8 * j + 3] * rs * ga.w);
;                         w.z = pk2(v[8 * j + 4] * rs * gb.x, v[8 * j + 5] * rs * gb.y); w.w = pk2(v[8 * j + 6] * rs * gb.z, v[8 * j + 7] * rs * gb.w);
;                         *((u32x4*)(orow + half * 1024) + lane + 64 * j) = w; }
	v_add_f32_dpp v24, v24, v24 quad_perm:[2,3,0,1] row_mask:0xf bank_mask:0xf
	s_nop 1
	v_add_f32_dpp v24, v24, v24 row_half_mirror row_mask:0xf bank_mask:0xf
	s_nop 1
	v_add_f32_dpp v24, v24, v24 row_mirror row_mask:0xf bank_mask:0xf
	v_mov_b32_e32 v25, v24
	s_nop 1
	v_permlane16_swap_b32 v25, v24
	v_add_f32_e32 v24, v24, v25
	v_mov_b32_e32 v25, v24
	s_nop 1
	v_permlane32_swap_b32 v25, v24
	v_add_f32_e32 v24, v24, v25
	v_fmamk_f32 v24, v24, 0x3a800000, v68
	v_mul_f32_e32 v25, 0x4f800000, v24
	v_cmp_gt_f32_e32 vcc, s15, v24
	s_nop 1
	v_cndmask_b32_e32 v24, v24, v25, vcc
	v_sqrt_f32_e32 v25, v24
	s_nop 0
	v_add_u32_e32 v26, -1, v25
	v_add_u32_e32 v27, 1, v25
	v_fma_f32 v28, -v26, v25, v24
	v_fma_f32 v29, -v27, v25, v24
	v_cmp_ge_f32_e64 s[0:1], 0, v28
	s_nop 1
	v_cndmask_b32_e64 v25, v25, v26, s[0:1]
	v_cmp_lt_f32_e64 s[0:1], 0, v29
	s_nop 1
	v_cndmask_b32_e64 v25, v25, v27, s[0:1]
	v_mul_f32_e32 v26, 0x37800000, v25
	v_cndmask_b32_e32 v25, v25, v26, vcc
	v_cmp_class_f32_e32 vcc, v24, v69
	s_nop 1
	v_cndmask_b32_e32 v24, v25, v24, vcc
	v_div_scale_f32 v25, s[0:1], v24, v24, 1.0
	v_rcp_f32_e32 v26, v25
	v_div_scale_f32 v27, vcc, 1.0, v24, 1.0
	v_fma_f32 v28, -v25, v26, 1.0
	v_fmac_f32_e32 v26, v28, v26
	v_mul_f32_e32 v28, v27, v26
	v_fma_f32 v29, -v25, v28, v27
	v_fmac_f32_e32 v28, v29, v26
	v_fma_f32 v25, -v25, v28, v27
	v_div_fmas_f32 v25, v25, v26, v28
	v_div_fixup_f32 v24, v25, v24, 1.0
	v_pk_mul_f32 v[26:27], v[24:25], v[44:45] op_sel_hi:[0,1]
	v_pk_mul_f32 v[28:29], v[24:25], v[38:39] op_sel_hi:[0,1]
	v_pk_mul_f32 v[30:31], v[24:25], v[36:37] op_sel_hi:[0,1]
	v_pk_mul_f32 v[34:35], v[24:25], v[34:35] op_sel_hi:[0,1]
	v_pk_mul_f32 v[20:21], v[26:27], v[136:137]
	v_pk_mul_f32 v[22:23], v[28:29], v[138:139]
	v_pk_mul_f32 v[26:27], v[30:31], v[140:141]
	v_pk_mul_f32 v[28:29], v[34:35], v[142:143]
	v_cvt_pk_bf16_f32 v16, v20, v21
	v_cvt_pk_bf16_f32 v17, v22, v23
	v_cvt_pk_bf16_f32 v18, v26, v27
	v_cvt_pk_bf16_f32 v19, v28, v29
	global_store_dwordx4 v[42:43], v[16:19], off offset:2048
	s_nop 1
	s_nop 0
	v_pk_mul_f32 v[26:27], v[24:25], v[70:71] op_sel_hi:[0,1]
	v_pk_mul_f32 v[28:29], v[24:25], v[60:61] op_sel_hi:[0,1]
	v_pk_mul_f32 v[30:31], v[24:25], v[58:59] op_sel_hi:[0,1]
	v_pk_mul_f32 v[24:25], v[24:25], v[32:33] op_sel_hi:[0,1]
	v_pk_mul_f32 v[16:17], v[26:27], v[144:145]
	v_pk_mul_f32 v[18:19], v[28:29], v[146:147]
	v_pk_mul_f32 v[20:21], v[30:31], v[148:149]
	v_pk_mul_f32 v[22:23], v[24:25], v[150:151]
	v_cvt_pk_bf16_f32 v16, v16, v17
	v_cvt_pk_bf16_f32 v17, v18, v19
	v_cvt_pk_bf16_f32 v18, v20, v21
	v_cvt_pk_bf16_f32 v19, v22, v23
	global_store_dwordx4 v[42:43], v[16:19], off offset:3072
	s_nop 1
	s_cmp_gt_i32 s6, 0x807f
	s_cbranch_scc1 .LBB0_621
.LBB0_627:
	s_waitcnt vmcnt(4)
	v_lshlrev_b32_e32 v38, 16, v12
	v_and_b32_e32 v39, 0xffff0000, v12
	v_lshlrev_b32_e32 v34, 16, v13
	v_and_b32_e32 v35, 0xffff0000, v13
	v_pk_mul_f32 v[12:13], v[38:39], v[38:39]
	v_pk_mul_f32 v[36:37], v[34:35], v[34:35]
	v_add_f32_e32 v12, v12, v13
	v_lshlrev_b32_e32 v32, 16, v14
	v_and_b32_e32 v33, 0xffff0000, v14
	v_add_f32_e32 v12, v12, v36
	v_lshlrev_b32_e32 v28, 16, v15
	v_and_b32_e32 v29, 0xffff0000, v15
	v_pk_mul_f32 v[14:15], v[32:33], v[32:33]
	v_add_f32_e32 v12, v12, v37
	v_add_f32_e32 v12, v12, v14
	v_pk_mul_f32 v[30:31], v[28:29], v[28:29]
	v_add_f32_e32 v12, v12, v15
	v_lshlrev_b32_e32 v46, 16, v8
	v_and_b32_e32 v47, 0xffff0000, v8
	v_add_f32_e32 v12, v12, v30
	v_lshlrev_b32_e32 v42, 16, v9
	v_and_b32_e32 v43, 0xffff0000, v9
	v_pk_mul_f32 v[8:9], v[46:47], v[46:47]
	v_add_f32_e32 v12, v12, v31
	v_add_f32_e32 v8, v12, v8
	v_pk_mul_f32 v[44:45], v[42:43], v[42:43]
	v_add_f32_e32 v8, v8, v9
	v_lshlrev_b32_e32 v40, 16, v10
	v_and_b32_e32 v41, 0xffff0000, v10
	v_add_f32_e32 v8, v8, v44
	v_lshlrev_b32_e32 v24, 16, v11
	v_and_b32_e32 v25, 0xffff0000, v11
	v_pk_mul_f32 v[10:11], v[40:41], v[40:41]
	v_add_f32_e32 v8, v8, v45
	v_add_f32_e32 v8, v8, v10
	v_pk_mul_f32 v[26:27], v[24:25], v[24:25]
	v_add_f32_e32 v8, v8, v11
	v_add_f32_e32 v8, v8, v26
	v_add_f32_e32 v8, v8, v27
	s_ashr_i32 s7, s6, 31
	v_lshlrev_b32_e32 v36, 16, v0
	v_and_b32_e32 v37, 0xffff0000, v0
	v_pk_mul_f32 v[60:61], v[36:37], v[36:37]
	s_nop 1
	v_add_f32_dpp v8, v8, v8 quad_perm:[1,0,3,2] row_mask:0xf bank_mask:0xf
	s_nop 1
	v_add_f32_dpp v8, v8, v8 quad_perm:[2,3,0,1] row_mask:0xf bank_mask:0xf
	s_nop 1
	v_add_f32_dpp v8, v8, v8 row_half_mirror row_mask:0xf bank_mask:0xf
	s_nop 1
	v_add_f32_dpp v8, v8, v8 row_mirror row_mask:0xf bank_mask:0xf
	v_mov_b32_e32 v9, v8
	s_nop 1
	v_permlane16_swap_b32 v9, v8
	v_add_f32_e32 v8, v8, v9
	v_mov_b32_e32 v9, v8
	s_nop 1
	v_permlane32_swap_b32 v9, v8
	v_add_f32_e32 v8, v8, v9
	v_fmamk_f32 v8, v8, 0x3a800000, v68
	v_mul_f32_e32 v9, 0x4f800000, v8
	v_cmp_gt_f32_e32 vcc, s15, v8
	s_nop 1
	v_cndmask_b32_e32 v8, v8, v9, vcc
	v_sqrt_f32_e32 v9, v8
	s_nop 0
	v_add_u32_e32 v10, -1, v9
	v_fma_f32 v12, -v10, v9, v8
	v_add_u32_e32 v11, 1, v9
	v_cmp_ge_f32_e64 s[0:1], 0, v12
	s_nop 1
	v_cndmask_b32_e64 v10, v9, v10, s[0:1]
	v_fma_f32 v9, -v11, v9, v8
	v_cmp_lt_f32_e64 s[0:1], 0, v9
	s_nop 1
	v_cndmask_b32_e64 v9, v10, v11, s[0:1]
	v_mul_f32_e32 v10, 0x37800000, v9
	v_cndmask_b32_e32 v9, v9, v10, vcc
	v_cmp_class_f32_e32 vcc, v8, v69
	s_nop 1
	v_cndmask_b32_e32 v8, v9, v8, vcc
	v_div_scale_f32 v9, s[0:1], v8, v8, 1.0
	v_rcp_f32_e32 v10, v9
; __device__ __forceinline__ float wave_sum(float v) {
; #pragma unroll
;     for (int o = 1; o < 64; o <<= 1) v += __shfl_xor(v, o);
;     return v;
; }
; __global__ void __launch_bounds__(NTHR, 2) hymba_fwd(Params P) {
;     ...
;                 for (int half = 0; half < 2; ++half) {
;                     const float* gg = half ? P.sb_norm_g : P.ssd_norm_g;
;                     float v[16]; float s = 0.f;
; #pragma unroll
;                     for (int j = 0; j < 2; ++j) { const u32x4 qq = q[u][half][j];
;                         v[8 * j + 0] = bflo(qq.x); v[8 * j + 1] = bfhi(qq.x); v[8 * j + 2] = bflo(qq.y); v[8 * j + 3] = bfhi(qq.y); v[8 * j + 4] = bflo(qq.z); v[8 * j + 5] = bfhi(qq.z); v[8 * j + 6] = bflo(qq.w); v[8 * j + 7] = bfhi(qq.w); }
; #pragma unroll
;                     for (int j = 0; j < 16; ++j) s += v[j] * v[j];
;                     const float rs = 1.f / sqrtf(wave_sum(s) * (1.f / 1024.f) + EPS);
; #pragma unroll
;                     for (int j = 0; j < 2; ++j) { const f32x4 ga = *(const f32x4*)(gg + 8 * lane + 512 * j), gb = *(const f32x4*)(gg + 8 * lane + 512 * j + 4); u32x4 w;
;                         w.x = pk2(v[8 * j + 0] * rs * ga.x, v[8 * j + 1] * rs * ga.y); w.y = pk2(v[8 * j + 2] * rs * ga.z, v[8 * j + 3] * rs * ga.w);
;                         w.z = pk2(v[8 * j + 4] * rs * gb.x, v[8 * j + 5] * rs * gb.y); w.w = pk2(v[8 * j + 6] * rs * gb.z, v[8 * j + 7] * rs * gb.w);
;                         *((u32x4*)(orow + half * 1024) + lane + 64 * j) = w; }
	s_lshl_b64 s[0:1], s[6:7], 12
	v_lshl_add_u64 v[26:27], v[48:49], 0, s[0:1]
	v_fma_f32 v11, -v9, v10, 1.0
	v_fmac_f32_e32 v10, v11, v10
	v_div_scale_f32 v11, vcc, 1.0, v8, 1.0
	v_mul_f32_e32 v12, v11, v10
	v_fma_f32 v13, -v9, v12, v11
	v_fmac_f32_e32 v12, v13, v10
	v_fma_f32 v9, -v9, v12, v11
	v_div_fmas_f32 v9, v9, v10, v12
	v_div_fixup_f32 v30, v9, v8, 1.0
	v_pk_mul_f32 v[8:9], v[30:31], v[38:39] op_sel_hi:[0,1]
	v_pk_mul_f32 v[10:11], v[30:31], v[34:35] op_sel_hi:[0,1]
	v_pk_mul_f32 v[8:9], v[8:9], v[120:121]
	v_pk_mul_f32 v[10:11], v[10:11], v[122:123]
	v_cvt_pk_bf16_f32 v8, v8, v9
	v_cvt_pk_bf16_f32 v9, v10, v11
	v_pk_mul_f32 v[10:11], v[30:31], v[32:33] op_sel_hi:[0,1]
	v_pk_mul_f32 v[12:13], v[30:31], v[28:29] op_sel_hi:[0,1]
	v_pk_mul_f32 v[10:11], v[10:11], v[124:125]
	v_pk_mul_f32 v[12:13], v[12:13], v[126:127]
	v_cvt_pk_bf16_f32 v10, v10, v11
	v_cvt_pk_bf16_f32 v11, v12, v13
	global_store_dwordx4 v[26:27], v[8:11], off
	s_nop 1
	s_nop 0
	v_lshlrev_b32_e32 v28, 16, v4
	v_and_b32_e32 v29, 0xffff0000, v4
	v_lshlrev_b32_e32 v18, 16, v7
	v_and_b32_e32 v19, 0xffff0000, v7
	v_lshlrev_b32_e32 v20, 16, v6
	v_and_b32_e32 v21, 0xffff0000, v6
	v_lshlrev_b32_e32 v22, 16, v5
	v_and_b32_e32 v23, 0xffff0000, v5
	v_pk_mul_f32 v[6:7], v[28:29], v[28:29]
	v_pk_mul_f32 v[4:5], v[22:23], v[22:23]
	v_add_f32_e32 v6, v6, v7
	v_add_f32_e32 v4, v6, v4
	v_lshlrev_b32_e32 v16, 16, v3
	v_and_b32_e32 v17, 0xffff0000, v3
	v_lshlrev_b32_e32 v32, 16, v2
	v_and_b32_e32 v33, 0xffff0000, v2
	v_pk_mul_f32 v[2:3], v[20:21], v[20:21]
	v_add_f32_e32 v4, v4, v5
	v_add_f32_e32 v2, v4, v2
	v_lshlrev_b32_e32 v34, 16, v1
	v_and_b32_e32 v35, 0xffff0000, v1
	v_pk_mul_f32 v[0:1], v[18:19], v[18:19]
	v_add_f32_e32 v2, v2, v3
	v_add_f32_e32 v0, v2, v0
	v_add_f32_e32 v0, v0, v1
	v_add_f32_e32 v0, v0, v60
	v_pk_mul_f32 v[58:59], v[34:35], v[34:35]
	v_add_f32_e32 v0, v0, v61
	v_add_f32_e32 v0, v0, v58
	v_add_f32_e32 v31, v0, v59
	v_pk_mul_f32 v[0:1], v[30:31], v[46:47] op_sel_hi:[0,1]
	v_pk_mul_f32 v[2:3], v[30:31], v[42:43] op_sel_hi:[0,1]
	v_pk_mul_f32 v[4:5], v[30:31], v[40:41] op_sel_hi:[0,1]
	v_pk_mul_f32 v[6:7], v[30:31], v[24:25] op_sel_hi:[0,1]
	v_pk_mul_f32 v[44:45], v[32:33], v[32:33]
	v_pk_mul_f32 v[38:39], v[16:17], v[16:17]
	v_pk_mul_f32 v[0:1], v[0:1], v[128:129]
	v_pk_mul_f32 v[2:3], v[2:3], v[130:131]
	v_pk_mul_f32 v[4:5], v[4:5], v[132:133]
	v_pk_mul_f32 v[6:7], v[6:7], v[134:135]
	v_cvt_pk_bf16_f32 v0, v0, v1
	v_cvt_pk_bf16_f32 v1, v2, v3
	v_cvt_pk_bf16_f32 v2, v4, v5
	v_cvt_pk_bf16_f32 v3, v6, v7
	global_store_dwordx4 v[26:27], v[0:3], off offset:1024
	s_nop 1
	s_nop 0
	v_add_f32_e32 v8, v31, v44
	v_add_f32_e32 v8, v8, v45
	v_add_f32_e32 v8, v8, v38
	v_add_f32_e32 v8, v8, v39
	s_nop 1
	v_add_f32_dpp v8, v8, v8 quad_perm:[1,0,3,2] row_mask:0xf bank_mask:0xf
	s_nop 1
	v_add_f32_dpp v8, v8, v8 quad_perm:[2,3,0,1] row_mask:0xf bank_mask:0xf
	s_nop 1
	v_add_f32_dpp v8, v8, v8 row_half_mirror row_mask:0xf bank_mask:0xf
	s_nop 1
	v_add_f32_dpp v8, v8, v8 row_mirror row_mask:0xf bank_mask:0xf
	v_mov_b32_e32 v9, v8
	s_nop 1
	v_permlane16_swap_b32 v9, v8
	v_add_f32_e32 v8, v8, v9
	v_mov_b32_e32 v9, v8
	s_nop 1
	v_permlane32_swap_b32 v9, v8
	v_add_f32_e32 v8, v8, v9
	v_fmamk_f32 v8, v8, 0x3a800000, v68
	v_mul_f32_e32 v9, 0x4f800000, v8
	v_cmp_gt_f32_e32 vcc, s15, v8
	s_nop 1
	v_cndmask_b32_e32 v8, v8, v9, vcc
	v_sqrt_f32_e32 v9, v8
	s_nop 0
	v_add_u32_e32 v10, -1, v9
	v_add_u32_e32 v11, 1, v9
	v_fma_f32 v12, -v10, v9, v8
	v_fma_f32 v13, -v11, v9, v8
	v_cmp_ge_f32_e64 s[0:1], 0, v12
	s_nop 1
	v_cndmask_b32_e64 v9, v9, v10, s[0:1]
	v_cmp_lt_f32_e64 s[0:1], 0, v13
	s_nop 1
	v_cndmask_b32_e64 v9, v9, v11, s[0:1]
	v_mul_f32_e32 v10, 0x37800000, v9
	v_cndmask_b32_e32 v9, v9, v10, vcc
	v_cmp_class_f32_e32 vcc, v8, v69
	s_nop 1
	v_cndmask_b32_e32 v8, v9, v8, vcc
	v_div_scale_f32 v9, s[0:1], v8, v8, 1.0
	v_rcp_f32_e32 v10, v9
	v_div_scale_f32 v11, vcc, 1.0, v8, 1.0
	v_fma_f32 v12, -v9, v10, 1.0
	v_fmac_f32_e32 v10, v12, v10
	v_mul_f32_e32 v12, v11, v10
	v_fma_f32 v13, -v9, v12, v11
	v_fmac_f32_e32 v12, v13, v10
	v_fma_f32 v9, -v9, v12, v11
	v_div_fmas_f32 v9, v9, v10, v12
	v_div_fixup_f32 v8, v9, v8, 1.0
	v_pk_mul_f32 v[10:11], v[8:9], v[28:29] op_sel_hi:[0,1]
	v_pk_mul_f32 v[12:13], v[8:9], v[22:23] op_sel_hi:[0,1]
	v_pk_mul_f32 v[14:15], v[8:9], v[20:21] op_sel_hi:[0,1]
	v_pk_mul_f32 v[18:19], v[8:9], v[18:19] op_sel_hi:[0,1]
	v_pk_mul_f32 v[4:5], v[10:11], v[136:137]
	v_pk_mul_f32 v[6:7], v[12:13], v[138:139]
	v_pk_mul_f32 v[10:11], v[14:15], v[140:141]
	v_pk_mul_f32 v[12:13], v[18:19], v[142:143]
	v_cvt_pk_bf16_f32 v0, v4, v5
	v_cvt_pk_bf16_f32 v1, v6, v7
	v_cvt_pk_bf16_f32 v2, v10, v11
	v_cvt_pk_bf16_f32 v3, v12, v13
	global_store_dwordx4 v[26:27], v[0:3], off offset:2048
	s_nop 1
	s_nop 0
	v_pk_mul_f32 v[10:11], v[8:9], v[36:37] op_sel_hi:[0,1]
	v_pk_mul_f32 v[12:13], v[8:9], v[34:35] op_sel_hi:[0,1]
	v_pk_mul_f32 v[14:15], v[8:9], v[32:33] op_sel_hi:[0,1]
	v_pk_mul_f32 v[8:9], v[8:9], v[16:17] op_sel_hi:[0,1]
	v_pk_mul_f32 v[0:1], v[10:11], v[144:145]
	v_pk_mul_f32 v[2:3], v[12:13], v[146:147]
	v_pk_mul_f32 v[4:5], v[14:15], v[148:149]
	v_pk_mul_f32 v[6:7], v[8:9], v[150:151]
	v_cvt_pk_bf16_f32 v0, v0, v1
	v_cvt_pk_bf16_f32 v1, v2, v3
	v_cvt_pk_bf16_f32 v2, v4, v5
	v_cvt_pk_bf16_f32 v3, v6, v7
	global_store_dwordx4 v[26:27], v[0:3], off offset:3072
	s_nop 1
	s_branch .LBB0_621

; __device__ __forceinline__ void rms_store_bf16(const f32x4 (&v)[4], const float* g, bf16_t* orow, int lane) {
;     float s = 0.f;
; #pragma unroll
;     for (int j = 0; j < 4; ++j) s += (v[j].x * v[j].x + v[j].y * v[j].y) + (v[j].z * v[j].z + v[j].w * v[j].w);
;     const float rs = 1.f / sqrtf(wave_sum(s) * (1.f / 1024.f) + EPS);
;     unsigned long long* o8 = (unsigned long long*)orow + lane;
; #pragma unroll
;     for (int j = 0; j < 4; ++j) { const f32x4 gg = *((const f32x4*)g + lane + 64 * j);
;         o8[64 * j] = (unsigned long long)pk2(v[j].x * rs * gg.x, v[j].y * rs * gg.y) | ((unsigned long long)pk2(v[j].z * rs * gg.z, v[j].w * rs * gg.w) << 32); }
; }
; __global__ void __launch_bounds__(NTHR, 2) hymba_fwd(Params P) {
;     ...
;         for (int t0 = gw; t0 < TT; t0 += 2 * NGW) {
;             f32x4 m[2][4], xv[2][4]; int tt[2];
; #pragma unroll
;             for (int u = 0; u < 2; ++u) { const int t = t0 + u * NGW; tt[u] = t; const int tc = t < TT ? t : TT - 1;
;                 const int b = tc / LL, p = tc - b * LL;
;                 const float* src = (p < NMETA) ? P.meta + (size_t)p * 1024 : P.x + ((size_t)b * SEQ + p - NMETA) * 1024;
; #pragma unroll
;                 for (int j = 0; j < 4; ++j) { const u32x2 mq = __builtin_nontemporal_load((const u32x2*)(MIX + (size_t)tc * 1024) + lane + 64 * j);
;                     m[u][j] = (f32x4){bflo(mq.x), bfhi(mq.x), bflo(mq.y), bfhi(mq.y)}; xv[u][j] = __builtin_nontemporal_load((const f32x4*)src + lane + 64 * j); } }
; #pragma unroll
;             for (int u = 0; u < 2; ++u) { const int t = tt[u]; if (t >= TT) continue;
;                 float s = 0.f; f32x4 hv[4];
; #pragma unroll
;                 for (int j = 0; j < 4; ++j) s += (m[u][j].x * m[u][j].x + m[u][j].y * m[u][j].y) + (m[u][j].z * m[u][j].z + m[u][j].w * m[u][j].w);
;                 const float rs = 1.f / sqrtf(wave_sum(s) * (1.f / 1024.f) + EPS);
; #pragma unroll
;                 for (int j = 0; j < 4; ++j) { const f32x4 gg = *((const f32x4*)P.mix_post_g + lane + 64 * j);
;                     hv[j] = xv[u][j] + m[u][j] * rs * gg; u32x2 hq; hq.x = pk2(hv[j].x, hv[j].y); hq.y = pk2(hv[j].z, hv[j].w); __builtin_nontemporal_store(hq, (u32x2*)(H1 + (size_t)t * 1024) + lane + 64 * j); }
;                 rms_store_bf16(hv, P.ffn_pre_g, XN + (size_t)t * 1024, lane);
.LBB0_806:
	s_waitcnt vmcnt(5)
	v_and_b32_e32 v63, 0xffff0000, v6
	v_and_b32_e32 v65, 0xffff0000, v7
	v_lshlrev_b32_e32 v62, 16, v6
	v_lshlrev_b32_e32 v64, 16, v7
	s_waitcnt vmcnt(4)
	v_lshlrev_b32_e32 v66, 16, v4
	v_and_b32_e32 v69, 0xffff0000, v5
	v_and_b32_e32 v68, 0xffff0000, v4
	s_waitcnt vmcnt(2)
	v_lshlrev_b32_e32 v75, 16, v0
	v_and_b32_e32 v77, 0xffff0000, v0
	v_mul_f32_e32 v0, v65, v65
	v_mul_f32_e32 v4, v63, v63
	v_lshlrev_b32_e32 v67, 16, v5
	v_lshlrev_b32_e32 v70, 16, v2
	v_and_b32_e32 v71, 0xffff0000, v2
	v_lshlrev_b32_e32 v72, 16, v3
	v_and_b32_e32 v73, 0xffff0000, v3
	v_lshlrev_b32_e32 v78, 16, v1
	v_and_b32_e32 v79, 0xffff0000, v1
	v_pk_fma_f32 v[0:1], v[64:65], v[64:65], v[0:1] op_sel_hi:[1,1,0]
	v_pk_mul_f32 v[2:3], v[68:69], v[68:69]
	v_pk_fma_f32 v[4:5], v[62:63], v[62:63], v[4:5] op_sel_hi:[1,1,0]
	v_pk_fma_f32 v[2:3], v[66:67], v[66:67], v[2:3]
	v_mov_b32_e32 v74, v4
	v_mov_b32_e32 v6, v0
	v_mov_b32_e32 v7, v75
	v_mul_f32_e32 v8, v77, v77
	v_pk_add_f32 v[0:1], v[4:5], v[0:1]
	v_pk_mul_f32 v[4:5], v[74:75], v[6:7]
	v_pk_add_f32 v[2:3], v[2:3], v[2:3] op_sel:[0,1] op_sel_hi:[1,0]
	v_mov_b32_e32 v1, v5
	v_mov_b32_e32 v3, v8
	v_pk_add_f32 v[0:1], v[0:1], v[2:3]
	v_mul_f32_e32 v2, v71, v71
	v_mul_f32_e32 v4, v73, v73
	v_mul_f32_e32 v9, v78, v78
	v_mul_f32_e32 v10, v79, v79
	v_pk_fma_f32 v[2:3], v[70:71], v[70:71], v[2:3] op_sel_hi:[1,1,0]
	v_pk_fma_f32 v[4:5], v[72:73], v[72:73], v[4:5] op_sel_hi:[1,1,0]
	v_mov_b32_e32 v3, v9
	v_mov_b32_e32 v5, v10
	v_pk_add_f32 v[2:3], v[2:3], v[4:5]
	s_ashr_i32 s5, s4, 31
	v_pk_add_f32 v[0:1], v[0:1], v[2:3]
	s_lshl_b64 s[4:5], s[4:5], 11
	v_add_f32_e32 v0, v0, v1
	v_lshl_add_u64 v[80:81], v[32:33], 0, s[4:5]
	v_lshl_add_u64 v[82:83], v[152:153], 4, s[14:15]
	global_load_dwordx4 v[12:15], v[82:83], off nt
	global_load_dwordx4 v[4:7], v[82:83], off offset:1024 nt
	s_cmp_gt_i32 s8, 0x807f
	s_nop 1
	v_add_f32_dpp v0, v0, v0 quad_perm:[1,0,3,2] row_mask:0xf bank_mask:0xf
	s_nop 1
	v_add_f32_dpp v0, v0, v0 quad_perm:[2,3,0,1] row_mask:0xf bank_mask:0xf
	s_nop 1
	v_add_f32_dpp v0, v0, v0 row_half_mirror row_mask:0xf bank_mask:0xf
	s_nop 1
	v_add_f32_dpp v0, v0, v0 row_mirror row_mask:0xf bank_mask:0xf
	v_mov_b32_e32 v1, v0
	s_nop 1
	v_permlane16_swap_b32 v1, v0
	v_add_f32_e32 v0, v0, v1
	v_mov_b32_e32 v1, v0
	s_nop 1
	v_permlane32_swap_b32 v1, v0
	v_add_f32_e32 v0, v0, v1
	v_fmamk_f32 v0, v0, 0x3a800000, v56
	v_mul_f32_e32 v1, 0x4f800000, v0
	v_cmp_gt_f32_e32 vcc, s21, v0
	s_nop 1
	v_cndmask_b32_e32 v0, v0, v1, vcc
	v_sqrt_f32_e32 v1, v0
	s_nop 0
	v_add_u32_e32 v2, -1, v1
	v_fma_f32 v3, -v2, v1, v0
	v_cmp_ge_f32_e64 s[4:5], 0, v3
	v_add_u32_e32 v3, 1, v1
	s_nop 0
	v_cndmask_b32_e64 v2, v1, v2, s[4:5]
	v_fma_f32 v1, -v3, v1, v0
	v_cmp_lt_f32_e64 s[4:5], 0, v1
	s_nop 1
	v_cndmask_b32_e64 v1, v2, v3, s[4:5]
	v_mul_f32_e32 v2, 0x37800000, v1
	v_cndmask_b32_e32 v1, v1, v2, vcc
	v_cmp_class_f32_e32 vcc, v0, v57
	s_nop 1
	v_cndmask_b32_e32 v74, v1, v0, vcc
	v_div_scale_f32 v76, s[4:5], v74, v74, 1.0
	v_rcp_f32_e32 v84, v76
	global_load_dwordx2 v[46:47], v[80:81], off nt
	global_load_dwordx2 v[44:45], v[80:81], off offset:512 nt
	global_load_dwordx2 v[42:43], v[80:81], off offset:1024 nt
	global_load_dwordx2 v[48:49], v[80:81], off offset:1536 nt
	global_load_dwordx4 v[8:11], v[82:83], off offset:2048 nt
	global_load_dwordx4 v[0:3], v[82:83], off offset:3072 nt
	v_fma_f32 v80, -v76, v84, 1.0
	v_fmac_f32_e32 v84, v80, v84
	v_div_scale_f32 v80, vcc, 1.0, v74, 1.0
	v_mul_f32_e32 v81, v80, v84
	v_fma_f32 v82, -v76, v81, v80
	v_fmac_f32_e32 v81, v82, v84
	v_fma_f32 v76, -v76, v81, v80
	v_div_fmas_f32 v76, v76, v84, v81
	v_div_fixup_f32 v74, v76, v74, 1.0
	v_pk_mul_f32 v[62:63], v[74:75], v[62:63] op_sel_hi:[0,1]
	v_pk_mul_f32 v[64:65], v[74:75], v[64:65] op_sel_hi:[0,1]
	s_waitcnt vmcnt(8)
	v_pk_fma_f32 v[60:61], v[98:99], v[64:65], v[30:31]
	v_pk_fma_f32 v[58:59], v[96:97], v[62:63], v[28:29]
	v_lshl_add_u64 v[80:81], v[36:37], 0, s[12:13]
	v_cvt_pk_bf16_f32 v28, v58, v59
	v_cvt_pk_bf16_f32 v29, v60, v61
	global_store_dwordx2 v[80:81], v[28:29], off nt
	v_mov_b32_e32 v62, v66
	v_mov_b32_e32 v63, v68
	v_mov_b32_e32 v68, v67
	v_pk_mul_f32 v[62:63], v[74:75], v[62:63] op_sel_hi:[0,1]
	v_pk_mul_f32 v[64:65], v[74:75], v[68:69] op_sel_hi:[0,1]
	v_mov_b32_e32 v76, v75
	v_pk_mul_f32 v[66:67], v[60:61], v[60:61]
	v_pk_mul_f32 v[68:69], v[58:59], v[58:59]
	v_pk_fma_f32 v[30:31], v[102:103], v[64:65], v[26:27]
	v_pk_fma_f32 v[28:29], v[100:101], v[62:63], v[24:25]
	v_cvt_pk_bf16_f32 v25, v30, v31
	v_cvt_pk_bf16_f32 v24, v28, v29
	global_store_dwordx2 v[80:81], v[24:25], off offset:512 nt
	v_pk_mul_f32 v[62:63], v[74:75], v[70:71] op_sel_hi:[0,1]
	v_pk_mul_f32 v[64:65], v[74:75], v[72:73] op_sel_hi:[0,1]
	v_pk_mov_b32 v[70:71], v[68:69], v[66:67] op_sel:[1,0]
	v_mov_b32_e32 v69, v67
	v_pk_add_f32 v[66:67], v[70:71], v[68:69]
	v_pk_mul_f32 v[68:69], v[28:29], v[28:29]
	v_pk_mul_f32 v[70:71], v[30:31], v[30:31]
	v_pk_add_f32 v[66:67], v[66:67], v[66:67] op_sel_hi:[0,1]
	v_pk_mov_b32 v[72:73], v[68:69], v[70:71] op_sel:[1,0]
	v_mov_b32_e32 v69, v71
	v_pk_add_f32 v[68:69], v[72:73], v[68:69]
	v_pk_fma_f32 v[26:27], v[106:107], v[64:65], v[22:23]
	v_pk_fma_f32 v[24:25], v[104:105], v[62:63], v[20:21]
	v_cvt_pk_bf16_f32 v21, v26, v27
	v_cvt_pk_bf16_f32 v20, v24, v25
	global_store_dwordx2 v[80:81], v[20:21], off offset:1024 nt
	v_pk_mul_f32 v[62:63], v[74:75], v[76:77] op_sel_hi:[0,1]
	v_pk_mul_f32 v[64:65], v[74:75], v[78:79] op_sel_hi:[0,1]
	v_pk_add_f32 v[68:69], v[68:69], v[68:69] op_sel_hi:[0,1]
	v_mul_f32_e32 v66, v24, v24
	v_mul_f32_e32 v68, v26, v26
	v_pk_fma_f32 v[70:71], v[24:25], v[24:25], v[66:67] op_sel_hi:[1,1,0]
; __device__ __forceinline__ void rms_store_bf16(const f32x4 (&v)[4], const float* g, bf16_t* orow, int lane) {
;     float s = 0.f;
; #pragma unroll
;     for (int j = 0; j < 4; ++j) s += (v[j].x * v[j].x + v[j].y * v[j].y) + (v[j].z * v[j].z + v[j].w * v[j].w);
;     const float rs = 1.f / sqrtf(wave_sum(s) * (1.f / 1024.f) + EPS);
;     unsigned long long* o8 = (unsigned long long*)orow + lane;
; #pragma unroll
;     for (int j = 0; j < 4; ++j) { const f32x4 gg = *((const f32x4*)g + lane + 64 * j);
;         o8[64 * j] = (unsigned long long)pk2(v[j].x * rs * gg.x, v[j].y * rs * gg.y) | ((unsigned long long)pk2(v[j].z * rs * gg.z, v[j].w * rs * gg.w) << 32); }
; }
; __global__ void __launch_bounds__(NTHR, 2) hymba_fwd(Params P) {
;     ...
;                 float s = 0.f; f32x4 hv[4];
; #pragma unroll
;                 for (int j = 0; j < 4; ++j) s += (m[u][j].x * m[u][j].x + m[u][j].y * m[u][j].y) + (m[u][j].z * m[u][j].z + m[u][j].w * m[u][j].w);
;                 const float rs = 1.f / sqrtf(wave_sum(s) * (1.f / 1024.f) + EPS);
; #pragma unroll
;                 for (int j = 0; j < 4; ++j) { const f32x4 gg = *((const f32x4*)P.mix_post_g + lane + 64 * j);
;                     hv[j] = xv[u][j] + m[u][j] * rs * gg; u32x2 hq; hq.x = pk2(hv[j].x, hv[j].y); hq.y = pk2(hv[j].z, hv[j].w); __builtin_nontemporal_store(hq, (u32x2*)(H1 + (size_t)t * 1024) + lane + 64 * j); }
;                 rms_store_bf16(hv, P.ffn_pre_g, XN + (size_t)t * 1024, lane);
	v_pk_fma_f32 v[72:73], v[26:27], v[26:27], v[68:69] op_sel_hi:[1,1,0]
	v_pk_fma_f32 v[22:23], v[110:111], v[64:65], v[18:19]
	v_pk_fma_f32 v[20:21], v[108:109], v[62:63], v[16:17]
	v_cvt_pk_bf16_f32 v17, v22, v23
	v_cvt_pk_bf16_f32 v16, v20, v21
	global_store_dwordx2 v[80:81], v[16:17], off offset:1536 nt
	v_mul_f32_e32 v70, v20, v20
	v_mul_f32_e32 v72, v21, v21
	v_mul_f32_e32 v66, v22, v22
	v_mul_f32_e32 v68, v23, v23
	v_pk_add_f32 v[62:63], v[70:71], v[72:73]
	v_pk_add_f32 v[64:65], v[66:67], v[68:69]
	s_nop 0
	v_pk_add_f32 v[62:63], v[62:63], v[64:65]
	s_nop 0
	v_add_f32_e32 v62, v62, v63
	s_nop 1
	v_add_f32_dpp v62, v62, v62 quad_perm:[1,0,3,2] row_mask:0xf bank_mask:0xf
	s_nop 1
	v_add_f32_dpp v62, v62, v62 quad_perm:[2,3,0,1] row_mask:0xf bank_mask:0xf
	s_nop 1
	v_add_f32_dpp v62, v62, v62 row_half_mirror row_mask:0xf bank_mask:0xf
	s_nop 1
	v_add_f32_dpp v62, v62, v62 row_mirror row_mask:0xf bank_mask:0xf
	v_mov_b32_e32 v63, v62
	s_nop 1
	v_permlane16_swap_b32 v63, v62
	v_add_f32_e32 v62, v62, v63
	v_mov_b32_e32 v63, v62
	s_nop 1
	v_permlane32_swap_b32 v63, v62
	v_add_f32_e32 v62, v62, v63
	v_fmamk_f32 v62, v62, 0x3a800000, v56
	v_mul_f32_e32 v63, 0x4f800000, v62
	v_cmp_gt_f32_e32 vcc, s21, v62
	s_nop 1
	v_cndmask_b32_e32 v62, v62, v63, vcc
	v_sqrt_f32_e32 v63, v62
	s_nop 0
	v_add_u32_e32 v64, -1, v63
	v_add_u32_e32 v65, 1, v63
	v_fma_f32 v66, -v64, v63, v62
	v_fma_f32 v67, -v65, v63, v62
	v_cmp_ge_f32_e64 s[4:5], 0, v66
	s_nop 1
	v_cndmask_b32_e64 v63, v63, v64, s[4:5]
	v_cmp_lt_f32_e64 s[4:5], 0, v67
	s_nop 1
	v_cndmask_b32_e64 v63, v63, v65, s[4:5]
	v_mul_f32_e32 v64, 0x37800000, v63
	v_cndmask_b32_e32 v63, v63, v64, vcc
	v_cmp_class_f32_e32 vcc, v62, v57
	s_nop 1
	v_cndmask_b32_e32 v64, v63, v62, vcc
	v_div_scale_f32 v65, s[4:5], v64, v64, 1.0
	v_rcp_f32_e32 v66, v65
	v_div_scale_f32 v67, vcc, 1.0, v64, 1.0
	v_lshl_add_u64 v[62:63], v[38:39], 0, s[12:13]
	v_fma_f32 v68, -v65, v66, 1.0
	v_fmac_f32_e32 v66, v68, v66
	v_mul_f32_e32 v68, v67, v66
	v_fma_f32 v69, -v65, v68, v67
	v_fmac_f32_e32 v68, v69, v66
	v_fma_f32 v65, -v65, v68, v67
	v_div_fmas_f32 v65, v65, v66, v68
	v_div_fixup_f32 v64, v65, v64, 1.0
	v_pk_mul_f32 v[58:59], v[58:59], v[64:65] op_sel_hi:[1,0]
	v_pk_mul_f32 v[60:61], v[60:61], v[64:65] op_sel_hi:[1,0]
	v_pk_mul_f32 v[16:17], v[112:113], v[58:59]
	v_pk_mul_f32 v[18:19], v[114:115], v[60:61]
	v_cvt_pk_bf16_f32 v16, v16, v17
	v_cvt_pk_bf16_f32 v17, v18, v19
	global_store_dwordx2 v[62:63], v[16:17], off
	v_pk_mul_f32 v[28:29], v[28:29], v[64:65] op_sel_hi:[1,0]
	v_pk_mul_f32 v[30:31], v[30:31], v[64:65] op_sel_hi:[1,0]
	v_pk_mul_f32 v[24:25], v[24:25], v[64:65] op_sel_hi:[1,0]
	v_pk_mul_f32 v[26:27], v[26:27], v[64:65] op_sel_hi:[1,0]
	v_pk_mul_f32 v[20:21], v[20:21], v[64:65] op_sel_hi:[1,0]
	v_pk_mul_f32 v[22:23], v[22:23], v[64:65] op_sel_hi:[1,0]
	v_pk_mul_f32 v[16:17], v[116:117], v[28:29]
	v_pk_mul_f32 v[18:19], v[118:119], v[30:31]
	v_cvt_pk_bf16_f32 v16, v16, v17
	v_cvt_pk_bf16_f32 v17, v18, v19
	global_store_dwordx2 v[62:63], v[16:17], off offset:512
	v_pk_mul_f32 v[16:17], v[120:121], v[24:25]
	v_pk_mul_f32 v[18:19], v[122:123], v[26:27]
	v_cvt_pk_bf16_f32 v16, v16, v17
	v_cvt_pk_bf16_f32 v17, v18, v19
	global_store_dwordx2 v[62:63], v[16:17], off offset:1024
	v_pk_mul_f32 v[16:17], v[20:21], v[124:125]
	v_pk_mul_f32 v[18:19], v[22:23], v[126:127]
	v_cvt_pk_bf16_f32 v16, v16, v17
	v_cvt_pk_bf16_f32 v17, v18, v19
	global_store_dwordx2 v[62:63], v[16:17], off offset:1536
	s_cbranch_scc1 .LBB0_797
	s_waitcnt vmcnt(8)
	v_and_b32_e32 v27, 0xffff0000, v46
	v_and_b32_e32 v29, 0xffff0000, v47
	v_lshlrev_b32_e32 v21, 16, v48
	v_lshlrev_b32_e32 v26, 16, v46
	v_lshlrev_b32_e32 v28, 16, v47
	v_mul_f32_e32 v16, v29, v29
	v_lshlrev_b32_e32 v31, 16, v45
	v_lshlrev_b32_e32 v30, 16, v44
	v_and_b32_e32 v45, 0xffff0000, v45
	v_and_b32_e32 v44, 0xffff0000, v44
	v_mul_f32_e32 v20, v27, v27
	v_and_b32_e32 v23, 0xffff0000, v48
	v_lshlrev_b32_e32 v24, 16, v49
	v_and_b32_e32 v25, 0xffff0000, v49
	v_pk_fma_f32 v[16:17], v[28:29], v[28:29], v[16:17] op_sel_hi:[1,1,0]
	v_pk_mul_f32 v[18:19], v[44:45], v[44:45]
	v_pk_fma_f32 v[48:49], v[26:27], v[26:27], v[20:21] op_sel_hi:[1,1,0]
	v_pk_fma_f32 v[18:19], v[30:31], v[30:31], v[18:19]
	v_mov_b32_e32 v20, v48
	v_mov_b32_e32 v58, v16
	v_mov_b32_e32 v59, v21
	v_mul_f32_e32 v22, v23, v23
	v_pk_add_f32 v[16:17], v[48:49], v[16:17]
	v_pk_mul_f32 v[48:49], v[20:21], v[58:59]
	v_pk_add_f32 v[18:19], v[18:19], v[18:19] op_sel:[0,1] op_sel_hi:[1,0]
	v_lshlrev_b32_e32 v46, 16, v42
	v_and_b32_e32 v47, 0xffff0000, v42
	v_lshlrev_b32_e32 v42, 16, v43
	v_and_b32_e32 v43, 0xffff0000, v43
	v_mov_b32_e32 v17, v49
	v_mov_b32_e32 v19, v22
	v_pk_add_f32 v[16:17], v[16:17], v[18:19]
	v_mul_f32_e32 v18, v47, v47
	v_mul_f32_e32 v20, v43, v43
	v_mul_f32_e32 v60, v24, v24
	v_mul_f32_e32 v61, v25, v25
	v_pk_fma_f32 v[18:19], v[46:47], v[46:47], v[18:19] op_sel_hi:[1,1,0]
	v_pk_fma_f32 v[48:49], v[42:43], v[42:43], v[20:21] op_sel_hi:[1,1,0]
	v_mov_b32_e32 v19, v60
	v_mov_b32_e32 v49, v61
	v_pk_add_f32 v[18:19], v[18:19], v[48:49]
	s_ashr_i32 s9, s8, 31
	v_pk_add_f32 v[48:49], v[16:17], v[18:19]
	v_add_f32_e32 v20, v48, v49
	s_lshl_b64 s[8:9], s[8:9], 11
	s_nop 1
	v_add_f32_dpp v20, v20, v20 quad_perm:[1,0,3,2] row_mask:0xf bank_mask:0xf
	s_nop 1
	v_add_f32_dpp v20, v20, v20 quad_perm:[2,3,0,1] row_mask:0xf bank_mask:0xf
	s_nop 1
	v_add_f32_dpp v20, v20, v20 row_half_mirror row_mask:0xf bank_mask:0xf
	s_nop 1
	v_add_f32_dpp v20, v20, v20 row_mirror row_mask:0xf bank_mask:0xf
	v_mov_b32_e32 v22, v20
	s_nop 1
	v_permlane16_swap_b32 v22, v20
	v_add_f32_e32 v20, v20, v22
	v_mov_b32_e32 v22, v20
	s_nop 1
; __device__ __forceinline__ void rms_store_bf16(const f32x4 (&v)[4], const float* g, bf16_t* orow, int lane) {
;     float s = 0.f;
; #pragma unroll
;     for (int j = 0; j < 4; ++j) s += (v[j].x * v[j].x + v[j].y * v[j].y) + (v[j].z * v[j].z + v[j].w * v[j].w);
;     const float rs = 1.f / sqrtf(wave_sum(s) * (1.f / 1024.f) + EPS);
;     unsigned long long* o8 = (unsigned long long*)orow + lane;
; #pragma unroll
;     for (int j = 0; j < 4; ++j) { const f32x4 gg = *((const f32x4*)g + lane + 64 * j);
;         o8[64 * j] = (unsigned long long)pk2(v[j].x * rs * gg.x, v[j].y * rs * gg.y) | ((unsigned long long)pk2(v[j].z * rs * gg.z, v[j].w * rs * gg.w) << 32); }
; }
; __global__ void __launch_bounds__(NTHR, 2) hymba_fwd(Params P) {
;     ...
;                 float s = 0.f; f32x4 hv[4];
; #pragma unroll
;                 for (int j = 0; j < 4; ++j) s += (m[u][j].x * m[u][j].x + m[u][j].y * m[u][j].y) + (m[u][j].z * m[u][j].z + m[u][j].w * m[u][j].w);
;                 const float rs = 1.f / sqrtf(wave_sum(s) * (1.f / 1024.f) + EPS);
; #pragma unroll
;                 for (int j = 0; j < 4; ++j) { const f32x4 gg = *((const f32x4*)P.mix_post_g + lane + 64 * j);
;                     hv[j] = xv[u][j] + m[u][j] * rs * gg; u32x2 hq; hq.x = pk2(hv[j].x, hv[j].y); hq.y = pk2(hv[j].z, hv[j].w); __builtin_nontemporal_store(hq, (u32x2*)(H1 + (size_t)t * 1024) + lane + 64 * j); }
;                 rms_store_bf16(hv, P.ffn_pre_g, XN + (size_t)t * 1024, lane);
	v_permlane32_swap_b32 v22, v20
	v_add_f32_e32 v20, v20, v22
	v_fmamk_f32 v20, v20, 0x3a800000, v56
	v_mul_f32_e32 v22, 0x4f800000, v20
	v_cmp_gt_f32_e32 vcc, s21, v20
	s_nop 1
	v_cndmask_b32_e32 v20, v20, v22, vcc
	v_sqrt_f32_e32 v22, v20
	s_nop 0
	v_add_u32_e32 v48, -1, v22
	v_fma_f32 v49, -v48, v22, v20
	v_cmp_ge_f32_e64 s[4:5], 0, v49
	v_add_u32_e32 v49, 1, v22
	s_nop 0
	v_cndmask_b32_e64 v48, v22, v48, s[4:5]
	v_fma_f32 v22, -v49, v22, v20
	v_cmp_lt_f32_e64 s[4:5], 0, v22
	s_nop 1
	v_cndmask_b32_e64 v22, v48, v49, s[4:5]
	v_mul_f32_e32 v48, 0x37800000, v22
	v_cndmask_b32_e32 v22, v22, v48, vcc
	v_cmp_class_f32_e32 vcc, v20, v57
	s_nop 1
	v_cndmask_b32_e32 v20, v22, v20, vcc
	v_div_scale_f32 v22, s[4:5], v20, v20, 1.0
	v_rcp_f32_e32 v48, v22
	s_nop 0
	v_fma_f32 v49, -v22, v48, 1.0
	v_fmac_f32_e32 v48, v49, v48
	v_div_scale_f32 v49, vcc, 1.0, v20, 1.0
	v_mul_f32_e32 v58, v49, v48
	v_fma_f32 v59, -v22, v58, v49
	v_fmac_f32_e32 v58, v59, v48
	v_fma_f32 v22, -v22, v58, v49
	v_div_fmas_f32 v22, v22, v48, v58
	v_div_fixup_f32 v20, v22, v20, 1.0
	v_pk_mul_f32 v[26:27], v[20:21], v[26:27] op_sel_hi:[0,1]
	v_pk_mul_f32 v[28:29], v[20:21], v[28:29] op_sel_hi:[0,1]
	v_pk_fma_f32 v[18:19], v[98:99], v[28:29], v[14:15]
	v_pk_fma_f32 v[16:17], v[96:97], v[26:27], v[12:13]
	v_lshl_add_u64 v[48:49], v[36:37], 0, s[8:9]
	v_cvt_pk_bf16_f32 v12, v16, v17
	v_cvt_pk_bf16_f32 v13, v18, v19
	global_store_dwordx2 v[48:49], v[12:13], off nt
	v_mov_b32_e32 v26, v30
	v_mov_b32_e32 v27, v44
	v_mov_b32_e32 v44, v31
	v_pk_mul_f32 v[26:27], v[20:21], v[26:27] op_sel_hi:[0,1]
	v_pk_mul_f32 v[28:29], v[20:21], v[44:45] op_sel_hi:[0,1]
	v_mov_b32_e32 v22, v21
	v_pk_mul_f32 v[22:23], v[20:21], v[22:23] op_sel_hi:[0,1]
	v_pk_fma_f32 v[14:15], v[102:103], v[28:29], v[6:7]
	v_pk_fma_f32 v[12:13], v[100:101], v[26:27], v[4:5]
	v_cvt_pk_bf16_f32 v5, v14, v15
	v_cvt_pk_bf16_f32 v4, v12, v13
	global_store_dwordx2 v[48:49], v[4:5], off offset:512 nt
	v_pk_mul_f32 v[26:27], v[20:21], v[46:47] op_sel_hi:[0,1]
	v_pk_mul_f32 v[28:29], v[20:21], v[42:43] op_sel_hi:[0,1]
	v_pk_mul_f32 v[20:21], v[20:21], v[24:25] op_sel_hi:[0,1]
	v_pk_mul_f32 v[24:25], v[18:19], v[18:19]
	v_pk_fma_f32 v[10:11], v[106:107], v[28:29], v[10:11]
	v_pk_fma_f32 v[8:9], v[104:105], v[26:27], v[8:9]
	v_cvt_pk_bf16_f32 v5, v10, v11
	v_cvt_pk_bf16_f32 v4, v8, v9
	global_store_dwordx2 v[48:49], v[4:5], off offset:1024 nt
	v_pk_mul_f32 v[26:27], v[16:17], v[16:17]
	v_pk_fma_f32 v[6:7], v[110:111], v[20:21], v[2:3]
	v_pk_fma_f32 v[4:5], v[108:109], v[22:23], v[0:1]
	v_cvt_pk_bf16_f32 v1, v6, v7
	v_cvt_pk_bf16_f32 v0, v4, v5
	global_store_dwordx2 v[48:49], v[0:1], off offset:1536 nt
	v_pk_mov_b32 v[28:29], v[26:27], v[24:25] op_sel:[1,0]
	v_mov_b32_e32 v27, v25
	v_pk_add_f32 v[24:25], v[28:29], v[26:27]
	v_pk_mul_f32 v[26:27], v[12:13], v[12:13]
	v_pk_mul_f32 v[28:29], v[14:15], v[14:15]
	v_pk_add_f32 v[24:25], v[24:25], v[24:25] op_sel_hi:[0,1]
	v_pk_mov_b32 v[30:31], v[26:27], v[28:29] op_sel:[1,0]
	v_mov_b32_e32 v27, v29
	v_pk_add_f32 v[26:27], v[30:31], v[26:27]
	v_mul_f32_e32 v24, v8, v8
	v_pk_add_f32 v[26:27], v[26:27], v[26:27] op_sel_hi:[0,1]
	v_mul_f32_e32 v26, v10, v10
	v_pk_fma_f32 v[28:29], v[8:9], v[8:9], v[24:25] op_sel_hi:[1,1,0]
	v_pk_fma_f32 v[30:31], v[10:11], v[10:11], v[26:27] op_sel_hi:[1,1,0]
	v_mul_f32_e32 v28, v4, v4
	v_mul_f32_e32 v30, v5, v5
	v_mul_f32_e32 v24, v6, v6
	v_mul_f32_e32 v26, v7, v7
	v_pk_add_f32 v[20:21], v[28:29], v[30:31]
	v_pk_add_f32 v[22:23], v[24:25], v[26:27]
	s_nop 0
	v_pk_add_f32 v[20:21], v[20:21], v[22:23]
	s_nop 0
	v_add_f32_e32 v20, v20, v21
	s_nop 1
	v_add_f32_dpp v20, v20, v20 quad_perm:[1,0,3,2] row_mask:0xf bank_mask:0xf
	s_nop 1
	v_add_f32_dpp v20, v20, v20 quad_perm:[2,3,0,1] row_mask:0xf bank_mask:0xf
	s_nop 1
	v_add_f32_dpp v20, v20, v20 row_half_mirror row_mask:0xf bank_mask:0xf
	s_nop 1
	v_add_f32_dpp v20, v20, v20 row_mirror row_mask:0xf bank_mask:0xf
	v_mov_b32_e32 v21, v20
	s_nop 1
	v_permlane16_swap_b32 v21, v20
	v_add_f32_e32 v20, v20, v21
	v_mov_b32_e32 v21, v20
	s_nop 1
	v_permlane32_swap_b32 v21, v20
	v_add_f32_e32 v20, v20, v21
	v_fmamk_f32 v20, v20, 0x3a800000, v56
	v_mul_f32_e32 v21, 0x4f800000, v20
	v_cmp_gt_f32_e32 vcc, s21, v20
	s_nop 1
	v_cndmask_b32_e32 v20, v20, v21, vcc
	v_sqrt_f32_e32 v21, v20
	s_nop 0
	v_add_u32_e32 v22, -1, v21
	v_add_u32_e32 v23, 1, v21
	v_fma_f32 v24, -v22, v21, v20
	v_fma_f32 v25, -v23, v21, v20
	v_cmp_ge_f32_e64 s[4:5], 0, v24
	s_nop 1
	v_cndmask_b32_e64 v21, v21, v22, s[4:5]
	v_cmp_lt_f32_e64 s[4:5], 0, v25
	s_nop 1
	v_cndmask_b32_e64 v21, v21, v23, s[4:5]
	v_mul_f32_e32 v22, 0x37800000, v21
	v_cndmask_b32_e32 v21, v21, v22, vcc
	v_cmp_class_f32_e32 vcc, v20, v57
	s_nop 1
	v_cndmask_b32_e32 v22, v21, v20, vcc
	v_div_scale_f32 v23, s[4:5], v22, v22, 1.0
	v_rcp_f32_e32 v24, v23
	v_div_scale_f32 v25, vcc, 1.0, v22, 1.0
	v_lshl_add_u64 v[20:21], v[38:39], 0, s[8:9]
	v_fma_f32 v26, -v23, v24, 1.0
	v_fmac_f32_e32 v24, v26, v24
	v_mul_f32_e32 v26, v25, v24
	v_fma_f32 v27, -v23, v26, v25
	v_fmac_f32_e32 v26, v27, v24
	v_fma_f32 v23, -v23, v26, v25
	v_div_fmas_f32 v23, v23, v24, v26
	v_div_fixup_f32 v22, v23, v22, 1.0
	v_pk_mul_f32 v[16:17], v[16:17], v[22:23] op_sel_hi:[1,0]
	v_pk_mul_f32 v[18:19], v[18:19], v[22:23] op_sel_hi:[1,0]
	v_pk_mul_f32 v[0:1], v[112:113], v[16:17]
	v_pk_mul_f32 v[2:3], v[114:115], v[18:19]
	v_cvt_pk_bf16_f32 v0, v0, v1
	v_cvt_pk_bf16_f32 v1, v2, v3
	global_store_dwordx2 v[20:21], v[0:1], off
	v_pk_mul_f32 v[12:13], v[12:13], v[22:23] op_sel_hi:[1,0]
	v_pk_mul_f32 v[14:15], v[14:15], v[22:23] op_sel_hi:[1,0]
	v_pk_mul_f32 v[8:9], v[8:9], v[22:23] op_sel_hi:[1,0]
	v_pk_mul_f32 v[10:11], v[10:11], v[22:23] op_sel_hi:[1,0]
	v_pk_mul_f32 v[4:5], v[4:5], v[22:23] op_sel_hi:[1,0]
	v_pk_mul_f32 v[6:7], v[6:7], v[22:23] op_sel_hi:[1,0]
	v_pk_mul_f32 v[0:1], v[116:117], v[12:13]
	v_pk_mul_f32 v[2:3], v[118:119], v[14:15]
	v_cvt_pk_bf16_f32 v0, v0, v1
	v_cvt_pk_bf16_f32 v1, v2, v3
	global_store_dwordx2 v[20:21], v[0:1], off offset:512
	v_pk_mul_f32 v[0:1], v[120:121], v[8:9]
	v_pk_mul_f32 v[2:3], v[122:123], v[10:11]
	v_cvt_pk_bf16_f32 v0, v0, v1
	v_cvt_pk_bf16_f32 v1, v2, v3
	global_store_dwordx2 v[20:21], v[0:1], off offset:1024
	v_pk_mul_f32 v[0:1], v[4:5], v[124:125]
	v_pk_mul_f32 v[2:3], v[6:7], v[126:127]
	v_cvt_pk_bf16_f32 v0, v0, v1
	v_cvt_pk_bf16_f32 v1, v2, v3
	global_store_dwordx2 v[20:21], v[0:1], off offset:1536
	s_branch .LBB0_797

; __global__ void __launch_bounds__(NTHR, 2) hymba_fwd(Params P) {
;     ...
;         for (int t0 = gw; t0 < NB * SEQ; t0 += 2 * NGW) {
;             f32x4 f[2][4], hv[2][4];
; #pragma unroll
;             for (int u = 0; u < 2; ++u) { int tr = t0 + u * NGW; tr = tr < NB * SEQ ? tr : NB * SEQ - 1;
;                 const int b = tr / SEQ, s = tr - b * SEQ; const size_t t = (size_t)b * LL + NMETA + s;
; #pragma unroll
;                 for (int j = 0; j < 4; ++j) { const u32x2 fq2 = __builtin_nontemporal_load((const u32x2*)(FB + (size_t)tr * 1024) + lane + 64 * j);
;                     f[u][j] = (f32x4){bflo(fq2.x), bfhi(fq2.x), bflo(fq2.y), bfhi(fq2.y)}; const u32x2 hq = __builtin_nontemporal_load((const u32x2*)(H1 + t * 1024) + lane + 64 * j); hv[u][j] = (f32x4){bflo(hq.x), bfhi(hq.x), bflo(hq.y), bfhi(hq.y)}; } }
; #pragma unroll
;             for (int u = 0; u < 2; ++u) { const int tr = t0 + u * NGW; if (tr >= NB * SEQ) continue;
;                 float ss = 0.f;
; #pragma unroll
;                 for (int j = 0; j < 4; ++j) ss += (f[u][j].x * f[u][j].x + f[u][j].y * f[u][j].y) + (f[u][j].z * f[u][j].z + f[u][j].w * f[u][j].w);
;                 const float rs = 1.f / sqrtf(wave_sum(ss) * (1.f / 1024.f) + EPS);
;                 f32x4* orow = (f32x4*)(P.out + (size_t)tr * 1024);
; #pragma unroll
;                 for (int j = 0; j < 4; ++j) { const f32x4 gg = *((const f32x4*)P.ffn_post_g + lane + 64 * j); __builtin_nontemporal_store(hv[u][j] + f[u][j] * rs * gg, &orow[lane + 64 * j]); }
.LBB0_1093:
	s_add_i32 s4, s89, s70
	s_min_i32 s6, s4, 0x7fff
	s_ashr_i32 s7, s6, 31
	s_lshr_b32 s0, s7, 20
	s_add_i32 s0, s6, s0
	s_ashr_i32 s1, s0, 12
	s_and_b32 s0, s0, 0xfffff000
	s_sub_i32 s0, s6, s0
	s_mul_hi_i32 s5, s1, 0x1010
	s_mulk_i32 s1, 0x1010
	s_ashr_i32 s11, s0, 31
	s_add_u32 s0, s1, s0
	s_addc_u32 s1, s5, s11
	s_ashr_i32 s71, s70, 31
	s_lshr_b32 s5, s71, 20
	s_add_i32 s5, s70, s5
	s_ashr_i32 s11, s5, 12
	s_and_b32 s5, s5, 0xfffff000
	s_sub_i32 s5, s70, s5
	s_lshl_b64 s[0:1], s[0:1], 11
	s_lshl_b64 s[6:7], s[6:7], 11
	s_mul_hi_i32 s13, s11, 0x1010
	s_mulk_i32 s11, 0x1010
	s_ashr_i32 s14, s5, 31
	s_add_u32 s12, s11, s5
	s_addc_u32 s13, s13, s14
	s_lshl_b64 s[14:15], s[70:71], 11
	v_lshl_add_u64 v[8:9], v[0:1], 0, s[14:15]
	s_lshl_b64 s[12:13], s[12:13], 11
	global_load_dwordx2 v[10:11], v[8:9], off offset:1536 nt
	global_load_dwordx2 v[12:13], v[8:9], off nt
	global_load_dwordx2 v[16:17], v[8:9], off offset:512 nt
	v_lshl_add_u64 v[14:15], v[2:3], 0, s[12:13]
	v_add_co_u32_e32 v18, vcc, s9, v14
	v_lshl_add_u64 v[56:57], v[14:15], 0, s[2:3]
	s_nop 0
	v_addc_co_u32_e32 v19, vcc, 0, v15, vcc
	global_load_dwordx2 v[36:37], v[18:19], off nt
	global_load_dwordx2 v[20:21], v[8:9], off offset:1024 nt
	s_waitcnt vmcnt(4)
	v_lshlrev_b32_e32 v39, 16, v10
	s_waitcnt vmcnt(3)
	v_and_b32_e32 v45, 0xffff0000, v12
	v_and_b32_e32 v47, 0xffff0000, v13
	v_mov_b32_e32 v9, v39
	v_lshlrev_b32_e32 v44, 16, v12
	v_lshlrev_b32_e32 v46, 16, v13
	s_waitcnt vmcnt(2)
	v_and_b32_e32 v51, 0xffff0000, v17
	v_and_b32_e32 v50, 0xffff0000, v16
	v_mul_f32_e32 v8, v47, v47
	v_mul_f32_e32 v12, v45, v45
	v_and_b32_e32 v41, 0xffff0000, v10
	v_lshlrev_b32_e32 v42, 16, v11
	v_and_b32_e32 v43, 0xffff0000, v11
	v_lshlrev_b32_e32 v49, 16, v17
	v_lshlrev_b32_e32 v48, 16, v16
	s_waitcnt vmcnt(0)
	v_lshlrev_b32_e32 v52, 16, v20
	v_and_b32_e32 v53, 0xffff0000, v20
	v_lshlrev_b32_e32 v54, 16, v21
	v_and_b32_e32 v55, 0xffff0000, v21
	v_pk_mul_f32 v[10:11], v[50:51], v[50:51]
	v_pk_fma_f32 v[20:21], v[46:47], v[46:47], v[8:9] op_sel_hi:[1,1,0]
	v_pk_fma_f32 v[12:13], v[44:45], v[44:45], v[12:13] op_sel_hi:[1,1,0]
	v_mul_f32_e32 v16, v53, v53
	v_mul_f32_e32 v18, v55, v55
	v_pk_fma_f32 v[10:11], v[48:49], v[48:49], v[10:11]
	v_mov_b32_e32 v38, v12
	v_mov_b32_e32 v8, v20
	v_mul_f32_e32 v22, v41, v41
	v_mul_f32_e32 v23, v42, v42
	v_mul_f32_e32 v40, v43, v43
	v_pk_fma_f32 v[16:17], v[52:53], v[52:53], v[16:17] op_sel_hi:[1,1,0]
	v_pk_fma_f32 v[18:19], v[54:55], v[54:55], v[18:19] op_sel_hi:[1,1,0]
	v_pk_add_f32 v[12:13], v[12:13], v[20:21]
	v_pk_add_f32 v[10:11], v[10:11], v[10:11] op_sel:[0,1] op_sel_hi:[1,0]
	v_pk_mul_f32 v[8:9], v[38:39], v[8:9]
	v_mov_b32_e32 v17, v23
	v_mov_b32_e32 v19, v40
	v_mov_b32_e32 v11, v22
	v_mov_b32_e32 v13, v9
	v_pk_add_f32 v[16:17], v[16:17], v[18:19]
	v_pk_add_f32 v[8:9], v[12:13], v[10:11]
	v_lshl_add_u64 v[10:11], v[2:3], 0, s[0:1]
	v_pk_add_f32 v[8:9], v[8:9], v[16:17]
	v_add_co_u32_e32 v60, vcc, s9, v10
	v_add_f32_e32 v8, v8, v9
	v_addc_co_u32_e32 v61, vcc, 0, v11, vcc
	v_lshl_add_u64 v[58:59], v[10:11], 0, s[2:3]
	s_lshl_b64 s[0:1], s[70:71], 12
	s_nop 1
	v_add_f32_dpp v12, v8, v8 quad_perm:[1,0,3,2] row_mask:0xf bank_mask:0xf
	v_lshl_add_u64 v[8:9], v[0:1], 0, s[6:7]
	global_load_dwordx2 v[20:21], v[8:9], off nt
	global_load_dwordx2 v[18:19], v[8:9], off offset:512 nt
	global_load_dwordx2 v[16:17], v[8:9], off offset:1024 nt
	global_load_dwordx2 v[22:23], v[8:9], off offset:1536 nt
	s_cmpk_gt_i32 s4, 0x7fff
	s_nop 1
	v_add_f32_dpp v12, v12, v12 quad_perm:[2,3,0,1] row_mask:0xf bank_mask:0xf
	s_nop 1
	v_add_f32_dpp v8, v12, v12 row_half_mirror row_mask:0xf bank_mask:0xf
	s_nop 1
	v_add_f32_dpp v38, v8, v8 row_mirror row_mask:0xf bank_mask:0xf
	global_load_dwordx2 v[14:15], v[60:61], off nt
	global_load_dwordx2 v[12:13], v[58:59], off offset:512 nt
	global_load_dwordx2 v[10:11], v[58:59], off offset:1024 nt
	global_load_dwordx2 v[8:9], v[58:59], off offset:1536 nt
	v_lshl_add_u64 v[58:59], v[6:7], 0, s[0:1]
	global_load_dwordx2 v[60:61], v[56:57], off offset:1536 nt
	global_load_dwordx2 v[62:63], v[56:57], off offset:1024 nt
	global_load_dwordx2 v[64:65], v[56:57], off offset:512 nt
	v_lshlrev_b32_e32 v56, 16, v36
	v_mov_b32_e32 v40, v38
	s_nop 1
	v_permlane16_swap_b32 v40, v38
	v_add_f32_e32 v38, v38, v40
	v_and_b32_e32 v57, 0xffff0000, v36
	v_lshlrev_b32_e32 v36, 16, v37
	v_and_b32_e32 v37, 0xffff0000, v37
	v_mov_b32_e32 v40, v38
	s_nop 1
	v_permlane32_swap_b32 v40, v38
	v_add_f32_e32 v38, v38, v40
	v_fmamk_f32 v38, v38, 0x3a800000, v30
	v_mul_f32_e32 v40, 0x4f800000, v38
	v_cmp_gt_f32_e32 vcc, s10, v38
	s_nop 1
	v_cndmask_b32_e32 v38, v38, v40, vcc
	v_sqrt_f32_e32 v40, v38
	s_nop 0
	v_add_u32_e32 v66, -1, v40
	v_add_u32_e32 v67, 1, v40
	v_fma_f32 v68, -v66, v40, v38
	v_fma_f32 v69, -v67, v40, v38
	v_cmp_ge_f32_e64 s[0:1], 0, v68
	s_nop 1
	v_cndmask_b32_e64 v40, v40, v66, s[0:1]
	v_cmp_lt_f32_e64 s[0:1], 0, v69
	s_nop 1
	v_cndmask_b32_e64 v40, v40, v67, s[0:1]
	v_mul_f32_e32 v66, 0x37800000, v40
	v_cndmask_b32_e32 v40, v40, v66, vcc
	v_cmp_class_f32_e32 vcc, v38, v31
	s_nop 1
	v_cndmask_b32_e32 v38, v40, v38, vcc
	v_div_scale_f32 v40, s[0:1], v38, v38, 1.0
	v_rcp_f32_e32 v66, v40
	v_div_scale_f32 v67, vcc, 1.0, v38, 1.0
	v_fma_f32 v68, -v40, v66, 1.0
	v_fmac_f32_e32 v66, v68, v66
	v_mul_f32_e32 v68, v67, v66
	v_fma_f32 v69, -v40, v68, v67
	v_fmac_f32_e32 v68, v69, v66
	v_fma_f32 v40, -v40, v68, v67
	v_div_fmas_f32 v40, v40, v66, v68
	v_div_fixup_f32 v38, v40, v38, 1.0
	v_pk_mul_f32 v[44:45], v[38:39], v[44:45] op_sel_hi:[0,1]
	v_pk_mul_f32 v[46:47], v[38:39], v[46:47] op_sel_hi:[0,1]
	s_waitcnt vmcnt(11)
; __global__ void __launch_bounds__(NTHR, 2) hymba_fwd(Params P) {
;     ...
;                 for (int j = 0; j < 4; ++j) { const u32x2 fq2 = __builtin_nontemporal_load((const u32x2*)(FB + (size_t)tr * 1024) + lane + 64 * j);
;                     f[u][j] = (f32x4){bflo(fq2.x), bfhi(fq2.x), bflo(fq2.y), bfhi(fq2.y)}; const u32x2 hq = __builtin_nontemporal_load((const u32x2*)(H1 + t * 1024) + lane + 64 * j); hv[u][j] = (f32x4){bflo(hq.x), bfhi(hq.x), bflo(hq.y), bfhi(hq.y)}; } }
; #pragma unroll
;             for (int u = 0; u < 2; ++u) { const int tr = t0 + u * NGW; if (tr >= NB * SEQ) continue;
;                 float ss = 0.f;
; #pragma unroll
;                 for (int j = 0; j < 4; ++j) ss += (f[u][j].x * f[u][j].x + f[u][j].y * f[u][j].y) + (f[u][j].z * f[u][j].z + f[u][j].w * f[u][j].w);
;                 const float rs = 1.f / sqrtf(wave_sum(ss) * (1.f / 1024.f) + EPS);
;                 f32x4* orow = (f32x4*)(P.out + (size_t)tr * 1024);
; #pragma unroll
;                 for (int j = 0; j < 4; ++j) { const f32x4 gg = *((const f32x4*)P.ffn_post_g + lane + 64 * j); __builtin_nontemporal_store(hv[u][j] + f[u][j] * rs * gg, &orow[lane + 64 * j]); }
;             }
	v_pk_fma_f32 v[34:35], v[82:83], v[46:47], v[36:37]
	v_pk_fma_f32 v[32:33], v[80:81], v[44:45], v[56:57]
	global_store_dwordx4 v[58:59], v[32:35], off nt
	s_nop 1
	v_mov_b32_e32 v46, v49
	v_mov_b32_e32 v47, v51
	v_mov_b32_e32 v49, v50
	v_pk_mul_f32 v[46:47], v[38:39], v[46:47] op_sel_hi:[0,1]
	v_pk_mul_f32 v[48:49], v[38:39], v[48:49] op_sel_hi:[0,1]
	v_mov_b32_e32 v40, v39
	v_pk_mul_f32 v[42:43], v[38:39], v[42:43] op_sel_hi:[0,1]
	s_waitcnt vmcnt(1)
	v_lshlrev_b32_e32 v36, 16, v64
	v_and_b32_e32 v37, 0xffff0000, v64
	v_lshlrev_b32_e32 v44, 16, v65
	v_and_b32_e32 v45, 0xffff0000, v65
	v_pk_fma_f32 v[32:33], v[84:85], v[48:49], v[36:37]
	v_pk_fma_f32 v[34:35], v[86:87], v[46:47], v[44:45]
	global_store_dwordx4 v[58:59], v[32:35], off offset:1024 nt
	s_nop 1
	v_lshlrev_b32_e32 v36, 16, v62
	v_and_b32_e32 v37, 0xffff0000, v62
	v_lshlrev_b32_e32 v44, 16, v63
	v_and_b32_e32 v45, 0xffff0000, v63
	v_pk_mul_f32 v[46:47], v[38:39], v[54:55] op_sel_hi:[0,1]
	v_pk_mul_f32 v[48:49], v[38:39], v[52:53] op_sel_hi:[0,1]
	v_pk_mul_f32 v[38:39], v[38:39], v[40:41] op_sel_hi:[0,1]
	v_pk_fma_f32 v[32:33], v[88:89], v[48:49], v[36:37]
	v_pk_fma_f32 v[34:35], v[90:91], v[46:47], v[44:45]
	global_store_dwordx4 v[58:59], v[32:35], off offset:2048 nt
	s_nop 1
	v_lshlrev_b32_e32 v36, 16, v60
	v_and_b32_e32 v37, 0xffff0000, v60
	v_lshlrev_b32_e32 v44, 16, v61
	v_and_b32_e32 v45, 0xffff0000, v61
	v_pk_fma_f32 v[32:33], v[92:93], v[38:39], v[36:37]
	v_pk_fma_f32 v[34:35], v[94:95], v[42:43], v[44:45]
	global_store_dwordx4 v[58:59], v[32:35], off offset:3072 nt
	s_nop 1
	s_cbranch_scc1 .LBB0_1092
	s_waitcnt vmcnt(4)
	v_lshlrev_b32_e32 v36, 16, v20
	v_and_b32_e32 v37, 0xffff0000, v20
	v_lshlrev_b32_e32 v20, 16, v21
	v_and_b32_e32 v21, 0xffff0000, v21
	v_lshlrev_b32_e32 v33, 16, v22
	v_mul_f32_e32 v32, v21, v21
	v_and_b32_e32 v43, 0xffff0000, v19
	v_and_b32_e32 v42, 0xffff0000, v18
	v_lshlrev_b32_e32 v44, 16, v16
	v_and_b32_e32 v45, 0xffff0000, v16
	v_mul_f32_e32 v16, v37, v37
	v_pk_fma_f32 v[38:39], v[20:21], v[20:21], v[32:33] op_sel_hi:[1,1,0]
	v_lshlrev_b32_e32 v41, 16, v19
	v_lshlrev_b32_e32 v40, 16, v18
	v_pk_mul_f32 v[18:19], v[42:43], v[42:43]
	v_lshlrev_b32_e32 v46, 16, v17
	v_and_b32_e32 v47, 0xffff0000, v17
	v_pk_fma_f32 v[16:17], v[36:37], v[36:37], v[16:17] op_sel_hi:[1,1,0]
	v_and_b32_e32 v35, 0xffff0000, v22
	v_pk_fma_f32 v[18:19], v[40:41], v[40:41], v[18:19]
	v_mov_b32_e32 v32, v16
	v_mov_b32_e32 v48, v38
	v_mov_b32_e32 v49, v33
	v_mul_f32_e32 v34, v35, v35
	v_pk_add_f32 v[16:17], v[16:17], v[38:39]
	v_pk_mul_f32 v[38:39], v[32:33], v[48:49]
	v_pk_add_f32 v[18:19], v[18:19], v[18:19] op_sel:[0,1] op_sel_hi:[1,0]
	v_mov_b32_e32 v17, v39
	v_mov_b32_e32 v19, v34
	v_lshlrev_b32_e32 v22, 16, v23
	v_and_b32_e32 v23, 0xffff0000, v23
	v_pk_add_f32 v[38:39], v[16:17], v[18:19]
	v_mul_f32_e32 v16, v45, v45
	v_mul_f32_e32 v18, v47, v47
	v_mul_f32_e32 v50, v22, v22
	v_mul_f32_e32 v51, v23, v23
	v_pk_fma_f32 v[16:17], v[44:45], v[44:45], v[16:17] op_sel_hi:[1,1,0]
	v_pk_fma_f32 v[18:19], v[46:47], v[46:47], v[18:19] op_sel_hi:[1,1,0]
	v_mov_b32_e32 v17, v50
	v_mov_b32_e32 v19, v51
	v_pk_add_f32 v[48:49], v[16:17], v[18:19]
	v_pk_add_f32 v[38:39], v[38:39], v[48:49]
	s_ashr_i32 s5, s4, 31
	v_add_f32_e32 v32, v38, v39
	v_lshlrev_b32_e32 v38, 16, v14
	s_nop 1
	v_add_f32_dpp v32, v32, v32 quad_perm:[1,0,3,2] row_mask:0xf bank_mask:0xf
	s_nop 1
	v_add_f32_dpp v32, v32, v32 quad_perm:[2,3,0,1] row_mask:0xf bank_mask:0xf
	s_nop 1
	v_add_f32_dpp v32, v32, v32 row_half_mirror row_mask:0xf bank_mask:0xf
	s_nop 1
	v_add_f32_dpp v32, v32, v32 row_mirror row_mask:0xf bank_mask:0xf
	v_mov_b32_e32 v34, v32
	s_nop 1
	v_permlane16_swap_b32 v34, v32
	v_add_f32_e32 v32, v32, v34
	v_mov_b32_e32 v34, v32
	s_nop 1
	v_permlane32_swap_b32 v34, v32
	v_add_f32_e32 v32, v32, v34
	v_fmamk_f32 v32, v32, 0x3a800000, v30
	v_mul_f32_e32 v34, 0x4f800000, v32
	v_cmp_gt_f32_e32 vcc, s10, v32
	s_nop 1
	v_cndmask_b32_e32 v32, v32, v34, vcc
	v_sqrt_f32_e32 v34, v32
	s_nop 0
	v_add_u32_e32 v39, -1, v34
	v_fma_f32 v48, -v39, v34, v32
	v_cmp_ge_f32_e64 s[0:1], 0, v48
	v_add_u32_e32 v48, 1, v34
	s_nop 0
	v_cndmask_b32_e64 v39, v34, v39, s[0:1]
	v_fma_f32 v34, -v48, v34, v32
	v_cmp_lt_f32_e64 s[0:1], 0, v34
	s_nop 1
	v_cndmask_b32_e64 v34, v39, v48, s[0:1]
	v_mul_f32_e32 v39, 0x37800000, v34
	v_cndmask_b32_e32 v34, v34, v39, vcc
	v_cmp_class_f32_e32 vcc, v32, v31
	v_and_b32_e32 v39, 0xffff0000, v14
	v_lshlrev_b32_e32 v14, 16, v15
	v_cndmask_b32_e32 v32, v34, v32, vcc
	v_div_scale_f32 v34, s[0:1], v32, v32, 1.0
	v_rcp_f32_e32 v48, v34
	v_and_b32_e32 v15, 0xffff0000, v15
	s_lshl_b64 s[0:1], s[4:5], 12
	v_fma_f32 v49, -v34, v48, 1.0
	v_fmac_f32_e32 v48, v49, v48
	v_div_scale_f32 v49, vcc, 1.0, v32, 1.0
	v_mul_f32_e32 v50, v49, v48
	v_fma_f32 v51, -v34, v50, v49
	v_fmac_f32_e32 v50, v51, v48
	v_fma_f32 v34, -v34, v50, v49
	v_div_fmas_f32 v34, v34, v48, v50
	v_div_fixup_f32 v32, v34, v32, 1.0
	v_pk_mul_f32 v[36:37], v[32:33], v[36:37] op_sel_hi:[0,1]
	v_pk_mul_f32 v[20:21], v[32:33], v[20:21] op_sel_hi:[0,1]
	v_pk_fma_f32 v[18:19], v[82:83], v[20:21], v[14:15]
	v_pk_fma_f32 v[16:17], v[80:81], v[36:37], v[38:39]
	v_lshl_add_u64 v[20:21], v[6:7], 0, s[0:1]
	global_store_dwordx4 v[20:21], v[16:19], off nt
	s_nop 1
	v_lshlrev_b32_e32 v36, 16, v13
	v_lshlrev_b32_e32 v18, 16, v12
	v_and_b32_e32 v19, 0xffff0000, v12
	v_and_b32_e32 v37, 0xffff0000, v13
	v_mov_b32_e32 v12, v41
	v_mov_b32_e32 v13, v43
	v_mov_b32_e32 v41, v42
	v_pk_mul_f32 v[38:39], v[32:33], v[12:13] op_sel_hi:[0,1]
	v_pk_mul_f32 v[12:13], v[32:33], v[40:41] op_sel_hi:[0,1]
	v_mov_b32_e32 v34, v33
	v_pk_fma_f32 v[12:13], v[84:85], v[12:13], v[18:19]
	v_pk_fma_f32 v[14:15], v[86:87], v[38:39], v[36:37]
	global_store_dwordx4 v[20:21], v[12:15], off offset:1024 nt
	s_nop 1
	v_lshlrev_b32_e32 v16, 16, v10
	v_and_b32_e32 v17, 0xffff0000, v10
	v_lshlrev_b32_e32 v18, 16, v11
	v_and_b32_e32 v19, 0xffff0000, v11
	v_pk_mul_f32 v[36:37], v[32:33], v[46:47] op_sel_hi:[0,1]
	v_pk_mul_f32 v[10:11], v[32:33], v[44:45] op_sel_hi:[0,1]
	v_pk_fma_f32 v[10:11], v[88:89], v[10:11], v[16:17]
	v_pk_fma_f32 v[12:13], v[90:91], v[36:37], v[18:19]
	global_store_dwordx4 v[20:21], v[10:13], off offset:2048 nt
	s_nop 1
	v_lshlrev_b32_e32 v14, 16, v8
	v_and_b32_e32 v15, 0xffff0000, v8
	v_lshlrev_b32_e32 v16, 16, v9
	v_and_b32_e32 v17, 0xffff0000, v9
	v_pk_mul_f32 v[18:19], v[32:33], v[22:23] op_sel_hi:[0,1]
	v_pk_mul_f32 v[8:9], v[32:33], v[34:35] op_sel_hi:[0,1]
	v_pk_fma_f32 v[8:9], v[92:93], v[8:9], v[14:15]
	v_pk_fma_f32 v[10:11], v[94:95], v[18:19], v[16:17]
	global_store_dwordx4 v[20:21], v[8:11], off offset:3072 nt
	s_nop 1
	s_branch .LBB0_1092
